# context-row small GEMMs: serialized load->vmcnt(0)->MFMA chains rewritten with distinct fragment registers and counted vmcnt (8 sites: 15-deep rolling window for K=2816, 8-deep batches for the 8-step
# baseline (speedup 1.0000x reference)
.LBB0_406:
	s_ashr_i32 s4, s0, 31
	s_lshr_b32 s4, s4, 27
	s_add_i32 s4, s0, s4
	s_andn2_b32 s4, s4, 31
	s_sub_i32 s5, s0, s4
	v_or_b32_e32 v0, s4, v26
	v_mad_i64_i32 v[24:25], s[14:15], v0, s87, v[16:17]
	v_lshl_or_b32 v20, s5, 5, v26
	v_mad_i64_i32 v[22:23], s[14:15], v20, s87, v[18:19]
	global_load_dwordx4 v[76:79], v[24:25], off
	global_load_dwordx4 v[80:83], v[22:23], off
	global_load_dwordx4 v[84:87], v[24:25], off offset:32
	global_load_dwordx4 v[88:91], v[22:23], off offset:32
	global_load_dwordx4 v[92:95], v[24:25], off offset:64
	global_load_dwordx4 v[96:99], v[22:23], off offset:64
	global_load_dwordx4 v[100:103], v[24:25], off offset:96
	global_load_dwordx4 v[104:107], v[22:23], off offset:96
	global_load_dwordx4 v[108:111], v[24:25], off offset:128
	global_load_dwordx4 v[112:115], v[22:23], off offset:128
	global_load_dwordx4 v[116:119], v[24:25], off offset:160
	global_load_dwordx4 v[120:123], v[22:23], off offset:160
	global_load_dwordx4 v[124:127], v[24:25], off offset:192
	global_load_dwordx4 v[128:131], v[22:23], off offset:192
	global_load_dwordx4 v[132:135], v[24:25], off offset:224
	global_load_dwordx4 v[136:139], v[22:23], off offset:224
	global_load_dwordx4 v[140:143], v[24:25], off offset:256
	global_load_dwordx4 v[144:147], v[22:23], off offset:256
	global_load_dwordx4 v[148:151], v[24:25], off offset:288
	global_load_dwordx4 v[152:155], v[22:23], off offset:288
	global_load_dwordx4 v[156:159], v[24:25], off offset:320
	global_load_dwordx4 v[160:163], v[22:23], off offset:320
	global_load_dwordx4 v[164:167], v[24:25], off offset:352
	global_load_dwordx4 v[168:171], v[22:23], off offset:352
	global_load_dwordx4 v[172:175], v[24:25], off offset:384
	global_load_dwordx4 v[176:179], v[22:23], off offset:384
	global_load_dwordx4 v[180:183], v[24:25], off offset:416
	global_load_dwordx4 v[184:187], v[22:23], off offset:416
	global_load_dwordx4 v[188:191], v[24:25], off offset:448
	global_load_dwordx4 v[192:195], v[22:23], off offset:448
	s_andn2_b64 vcc, exec, s[8:9]
	s_waitcnt vmcnt(28)
	v_mfma_f32_32x32x16_bf16 v[0:15], v[76:79], v[80:83], 0
	global_load_dwordx4 v[76:79], v[24:25], off offset:480
	global_load_dwordx4 v[80:83], v[22:23], off offset:480
	s_waitcnt vmcnt(28)
	v_mfma_f32_32x32x16_bf16 v[0:15], v[84:87], v[88:91], v[0:15]
	global_load_dwordx4 v[84:87], v[24:25], off offset:512
	global_load_dwordx4 v[88:91], v[22:23], off offset:512
	s_waitcnt vmcnt(28)
	v_mfma_f32_32x32x16_bf16 v[0:15], v[92:95], v[96:99], v[0:15]
	global_load_dwordx4 v[92:95], v[24:25], off offset:544
	global_load_dwordx4 v[96:99], v[22:23], off offset:544
	s_waitcnt vmcnt(28)
	v_mfma_f32_32x32x16_bf16 v[0:15], v[100:103], v[104:107], v[0:15]
	global_load_dwordx4 v[100:103], v[24:25], off offset:576
	global_load_dwordx4 v[104:107], v[22:23], off offset:576
	s_waitcnt vmcnt(28)
	v_mfma_f32_32x32x16_bf16 v[0:15], v[108:111], v[112:115], v[0:15]
	global_load_dwordx4 v[108:111], v[24:25], off offset:608
	global_load_dwordx4 v[112:115], v[22:23], off offset:608
	s_waitcnt vmcnt(28)
	v_mfma_f32_32x32x16_bf16 v[0:15], v[116:119], v[120:123], v[0:15]
	global_load_dwordx4 v[116:119], v[24:25], off offset:640
	global_load_dwordx4 v[120:123], v[22:23], off offset:640
	s_waitcnt vmcnt(28)
	v_mfma_f32_32x32x16_bf16 v[0:15], v[124:127], v[128:131], v[0:15]
	global_load_dwordx4 v[124:127], v[24:25], off offset:672
	global_load_dwordx4 v[128:131], v[22:23], off offset:672
	s_waitcnt vmcnt(28)
	v_mfma_f32_32x32x16_bf16 v[0:15], v[132:135], v[136:139], v[0:15]
	global_load_dwordx4 v[132:135], v[24:25], off offset:704
	global_load_dwordx4 v[136:139], v[22:23], off offset:704
	s_waitcnt vmcnt(28)
	v_mfma_f32_32x32x16_bf16 v[0:15], v[140:143], v[144:147], v[0:15]
	global_load_dwordx4 v[140:143], v[24:25], off offset:736
	global_load_dwordx4 v[144:147], v[22:23], off offset:736
	s_waitcnt vmcnt(28)
	v_mfma_f32_32x32x16_bf16 v[0:15], v[148:151], v[152:155], v[0:15]
	global_load_dwordx4 v[148:151], v[24:25], off offset:768
	global_load_dwordx4 v[152:155], v[22:23], off offset:768
	s_waitcnt vmcnt(28)
	v_mfma_f32_32x32x16_bf16 v[0:15], v[156:159], v[160:163], v[0:15]
	global_load_dwordx4 v[156:159], v[24:25], off offset:800
	global_load_dwordx4 v[160:163], v[22:23], off offset:800
	s_waitcnt vmcnt(28)
	v_mfma_f32_32x32x16_bf16 v[0:15], v[164:167], v[168:171], v[0:15]
	global_load_dwordx4 v[164:167], v[24:25], off offset:832
	global_load_dwordx4 v[168:171], v[22:23], off offset:832
	s_waitcnt vmcnt(28)
	v_mfma_f32_32x32x16_bf16 v[0:15], v[172:175], v[176:179], v[0:15]
	global_load_dwordx4 v[172:175], v[24:25], off offset:864
	global_load_dwordx4 v[176:179], v[22:23], off offset:864
	s_waitcnt vmcnt(28)
	v_mfma_f32_32x32x16_bf16 v[0:15], v[180:183], v[184:187], v[0:15]
	global_load_dwordx4 v[180:183], v[24:25], off offset:896
	global_load_dwordx4 v[184:187], v[22:23], off offset:896
	s_waitcnt vmcnt(28)
	v_mfma_f32_32x32x16_bf16 v[0:15], v[188:191], v[192:195], v[0:15]
	global_load_dwordx4 v[188:191], v[24:25], off offset:928
	global_load_dwordx4 v[192:195], v[22:23], off offset:928
	s_waitcnt vmcnt(28)
	v_mfma_f32_32x32x16_bf16 v[0:15], v[76:79], v[80:83], v[0:15]
	global_load_dwordx4 v[76:79], v[24:25], off offset:960
	global_load_dwordx4 v[80:83], v[22:23], off offset:960
	s_waitcnt vmcnt(28)
	v_mfma_f32_32x32x16_bf16 v[0:15], v[84:87], v[88:91], v[0:15]
	global_load_dwordx4 v[84:87], v[24:25], off offset:992
	global_load_dwordx4 v[88:91], v[22:23], off offset:992
	s_waitcnt vmcnt(28)
	v_mfma_f32_32x32x16_bf16 v[0:15], v[92:95], v[96:99], v[0:15]
	global_load_dwordx4 v[92:95], v[24:25], off offset:1024
	global_load_dwordx4 v[96:99], v[22:23], off offset:1024
	s_waitcnt vmcnt(28)
	v_mfma_f32_32x32x16_bf16 v[0:15], v[100:103], v[104:107], v[0:15]
	global_load_dwordx4 v[100:103], v[24:25], off offset:1056
	global_load_dwordx4 v[104:107], v[22:23], off offset:1056
	s_waitcnt vmcnt(28)
	v_mfma_f32_32x32x16_bf16 v[0:15], v[108:111], v[112:115], v[0:15]
	global_load_dwordx4 v[108:111], v[24:25], off offset:1088
	global_load_dwordx4 v[112:115], v[22:23], off offset:1088
	s_waitcnt vmcnt(28)
	v_mfma_f32_32x32x16_bf16 v[0:15], v[116:119], v[120:123], v[0:15]
	global_load_dwordx4 v[116:119], v[24:25], off offset:1120
	global_load_dwordx4 v[120:123], v[22:23], off offset:1120
	s_waitcnt vmcnt(28)
	v_mfma_f32_32x32x16_bf16 v[0:15], v[124:127], v[128:131], v[0:15]
	global_load_dwordx4 v[124:127], v[24:25], off offset:1152
	global_load_dwordx4 v[128:131], v[22:23], off offset:1152
	s_waitcnt vmcnt(28)
	v_mfma_f32_32x32x16_bf16 v[0:15], v[132:135], v[136:139], v[0:15]
	global_load_dwordx4 v[132:135], v[24:25], off offset:1184
	global_load_dwordx4 v[136:139], v[22:23], off offset:1184
	s_waitcnt vmcnt(28)
	v_mfma_f32_32x32x16_bf16 v[0:15], v[140:143], v[144:147], v[0:15]
	global_load_dwordx4 v[140:143], v[24:25], off offset:1216
	global_load_dwordx4 v[144:147], v[22:23], off offset:1216
	s_waitcnt vmcnt(28)
	v_mfma_f32_32x32x16_bf16 v[0:15], v[148:151], v[152:155], v[0:15]
	global_load_dwordx4 v[148:151], v[24:25], off offset:1248
	global_load_dwordx4 v[152:155], v[22:23], off offset:1248
	s_waitcnt vmcnt(28)
	v_mfma_f32_32x32x16_bf16 v[0:15], v[156:159], v[160:163], v[0:15]
	global_load_dwordx4 v[156:159], v[24:25], off offset:1280
	global_load_dwordx4 v[160:163], v[22:23], off offset:1280
	s_waitcnt vmcnt(28)
	v_mfma_f32_32x32x16_bf16 v[0:15], v[164:167], v[168:171], v[0:15]
	global_load_dwordx4 v[164:167], v[24:25], off offset:1312
	global_load_dwordx4 v[168:171], v[22:23], off offset:1312
	s_waitcnt vmcnt(28)
	v_mfma_f32_32x32x16_bf16 v[0:15], v[172:175], v[176:179], v[0:15]
	global_load_dwordx4 v[172:175], v[24:25], off offset:1344
	global_load_dwordx4 v[176:179], v[22:23], off offset:1344
	s_waitcnt vmcnt(28)
	v_mfma_f32_32x32x16_bf16 v[0:15], v[180:183], v[184:187], v[0:15]
	global_load_dwordx4 v[180:183], v[24:25], off offset:1376
	global_load_dwordx4 v[184:187], v[22:23], off offset:1376
	s_waitcnt vmcnt(28)
	v_mfma_f32_32x32x16_bf16 v[0:15], v[188:191], v[192:195], v[0:15]
	s_waitcnt vmcnt(26)
	v_mfma_f32_32x32x16_bf16 v[0:15], v[76:79], v[80:83], v[0:15]
	s_waitcnt vmcnt(24)
	v_mfma_f32_32x32x16_bf16 v[0:15], v[84:87], v[88:91], v[0:15]
	s_waitcnt vmcnt(22)
	v_mfma_f32_32x32x16_bf16 v[0:15], v[92:95], v[96:99], v[0:15]
	s_waitcnt vmcnt(20)
	v_mfma_f32_32x32x16_bf16 v[0:15], v[100:103], v[104:107], v[0:15]
	s_waitcnt vmcnt(18)
	v_mfma_f32_32x32x16_bf16 v[0:15], v[108:111], v[112:115], v[0:15]
	s_waitcnt vmcnt(16)
	v_mfma_f32_32x32x16_bf16 v[0:15], v[116:119], v[120:123], v[0:15]
	s_waitcnt vmcnt(14)
	v_mfma_f32_32x32x16_bf16 v[0:15], v[124:127], v[128:131], v[0:15]
	s_waitcnt vmcnt(12)
	v_mfma_f32_32x32x16_bf16 v[0:15], v[132:135], v[136:139], v[0:15]
	s_waitcnt vmcnt(10)
	v_mfma_f32_32x32x16_bf16 v[0:15], v[140:143], v[144:147], v[0:15]
	s_waitcnt vmcnt(8)
	v_mfma_f32_32x32x16_bf16 v[0:15], v[148:151], v[152:155], v[0:15]
	s_waitcnt vmcnt(6)
	v_mfma_f32_32x32x16_bf16 v[0:15], v[156:159], v[160:163], v[0:15]
	s_waitcnt vmcnt(4)
	v_mfma_f32_32x32x16_bf16 v[0:15], v[164:167], v[168:171], v[0:15]
	s_waitcnt vmcnt(2)
	v_mfma_f32_32x32x16_bf16 v[0:15], v[172:175], v[176:179], v[0:15]
	s_waitcnt vmcnt(0)
	v_mfma_f32_32x32x16_bf16 v[0:15], v[180:183], v[184:187], v[0:15]
	s_nop 11
	ds_write2st64_b32 v27, v0, v1 offset1:1
	ds_write2st64_b32 v27, v2, v3 offset0:2 offset1:3
	ds_write2st64_b32 v27, v4, v5 offset0:4 offset1:5
	ds_write2st64_b32 v27, v6, v7 offset0:6 offset1:7
	ds_write2st64_b32 v27, v8, v9 offset0:8 offset1:9
	ds_write2st64_b32 v27, v10, v11 offset0:10 offset1:11
	ds_write2st64_b32 v27, v12, v13 offset0:12 offset1:13
	ds_write2st64_b32 v27, v14, v15 offset0:14 offset1:15
	s_waitcnt lgkmcnt(0)
	s_barrier
	s_cbranch_vccnz .LBB0_405
	ds_read2st64_b32 v[4:5], v27 offset1:1
	ds_read2st64_b32 v[6:7], v27 offset0:16 offset1:17
	ds_read2st64_b32 v[8:9], v27 offset0:32 offset1:33
	ds_read2st64_b32 v[10:11], v27 offset0:48 offset1:49
	v_or_b32_e32 v2, s4, v28
	v_ashrrev_i32_e32 v21, 31, v20
	v_lshl_add_u64 v[0:1], v[20:21], 2, s[6:7]
	s_waitcnt lgkmcnt(2)
	v_add_f32_e32 v3, v4, v6
	s_waitcnt lgkmcnt(0)
	v_add_f32_e32 v4, v8, v10
	v_add_f32_e32 v4, v3, v4
	v_ashrrev_i32_e32 v3, 31, v2
	v_lshlrev_b64 v[12:13], 10, v[2:3]
	v_lshl_add_u64 v[12:13], v[12:13], 0, v[20:21]
	v_lshlrev_b64 v[12:13], 2, v[12:13]
	v_lshl_add_u64 v[14:15], s[12:13], 0, v[12:13]
	global_load_dword v3, v[14:15], off
	global_load_dword v6, v[0:1], off
	v_lshl_add_u64 v[12:13], s[10:11], 0, v[12:13]
	s_waitcnt vmcnt(0)
	v_mul_f32_e32 v6, 0.5, v6
	v_fmac_f32_e32 v3, v4, v6
	global_store_dword v[12:13], v3, off
	v_add_f32_e32 v3, v5, v7
	v_add_f32_e32 v4, v9, v11
	v_add_f32_e32 v3, v3, v4
	v_or_b32_e32 v4, 1, v2
	v_ashrrev_i32_e32 v5, 31, v4
	v_lshlrev_b64 v[4:5], 10, v[4:5]
	v_lshl_add_u64 v[4:5], v[4:5], 0, v[20:21]
	v_lshlrev_b64 v[4:5], 2, v[4:5]
	v_lshl_add_u64 v[6:7], s[12:13], 0, v[4:5]
	global_load_dword v6, v[6:7], off
	s_nop 0
	global_load_dword v7, v[0:1], off
	v_lshl_add_u64 v[4:5], s[10:11], 0, v[4:5]
	v_or_b32_e32 v12, 2, v2
	v_ashrrev_i32_e32 v13, 31, v12
	v_lshlrev_b64 v[12:13], 10, v[12:13]
	v_lshl_add_u64 v[12:13], v[12:13], 0, v[20:21]
	v_lshlrev_b64 v[12:13], 2, v[12:13]
	v_lshl_add_u64 v[14:15], s[12:13], 0, v[12:13]
	v_lshl_add_u64 v[12:13], s[10:11], 0, v[12:13]
	s_waitcnt vmcnt(0)
	v_mul_f32_e32 v7, 0.5, v7
	v_fmac_f32_e32 v6, v3, v7
	global_store_dword v[4:5], v6, off
	ds_read2st64_b32 v[4:5], v27 offset0:2 offset1:3
	ds_read2st64_b32 v[6:7], v27 offset0:18 offset1:19
	ds_read2st64_b32 v[8:9], v27 offset0:34 offset1:35
	ds_read2st64_b32 v[10:11], v27 offset0:50 offset1:51
	s_waitcnt lgkmcnt(2)
	v_add_f32_e32 v3, v4, v6
	s_waitcnt lgkmcnt(0)
	v_add_f32_e32 v4, v8, v10
	v_add_f32_e32 v3, v3, v4
	global_load_dword v4, v[14:15], off
	global_load_dword v6, v[0:1], off
	s_waitcnt vmcnt(0)
	v_mul_f32_e32 v6, 0.5, v6
	v_fmac_f32_e32 v4, v3, v6
	global_store_dword v[12:13], v4, off
	v_add_f32_e32 v3, v5, v7
	v_add_f32_e32 v4, v9, v11
	v_add_f32_e32 v3, v3, v4
	v_or_b32_e32 v4, 3, v2
	v_ashrrev_i32_e32 v5, 31, v4
	v_lshlrev_b64 v[4:5], 10, v[4:5]
	v_lshl_add_u64 v[4:5], v[4:5], 0, v[20:21]
	v_lshlrev_b64 v[4:5], 2, v[4:5]
	v_lshl_add_u64 v[6:7], s[12:13], 0, v[4:5]
	global_load_dword v6, v[6:7], off
	s_nop 0
	global_load_dword v7, v[0:1], off
	v_lshl_add_u64 v[4:5], s[10:11], 0, v[4:5]
	v_or_b32_e32 v12, 8, v2
	v_ashrrev_i32_e32 v13, 31, v12
	v_lshlrev_b64 v[12:13], 10, v[12:13]
	v_lshl_add_u64 v[12:13], v[12:13], 0, v[20:21]
	v_lshlrev_b64 v[12:13], 2, v[12:13]
	v_lshl_add_u64 v[14:15], s[12:13], 0, v[12:13]
	v_lshl_add_u64 v[12:13], s[10:11], 0, v[12:13]
	s_waitcnt vmcnt(0)
	v_mul_f32_e32 v7, 0.5, v7
	v_fmac_f32_e32 v6, v3, v7
	global_store_dword v[4:5], v6, off
	ds_read2st64_b32 v[4:5], v27 offset0:4 offset1:5
	ds_read2st64_b32 v[6:7], v27 offset0:20 offset1:21
	ds_read2st64_b32 v[8:9], v27 offset0:36 offset1:37
	ds_read2st64_b32 v[10:11], v27 offset0:52 offset1:53
	s_waitcnt lgkmcnt(2)
	v_add_f32_e32 v3, v4, v6
	s_waitcnt lgkmcnt(0)
	v_add_f32_e32 v4, v8, v10
	v_add_f32_e32 v3, v3, v4
	global_load_dword v4, v[14:15], off
	global_load_dword v6, v[0:1], off
	s_waitcnt vmcnt(0)
	v_mul_f32_e32 v6, 0.5, v6
	v_fmac_f32_e32 v4, v3, v6
	global_store_dword v[12:13], v4, off
	v_add_f32_e32 v3, v5, v7
	v_add_f32_e32 v4, v9, v11
	v_add_f32_e32 v3, v3, v4
	v_or_b32_e32 v4, 9, v2
	v_ashrrev_i32_e32 v5, 31, v4
	v_lshlrev_b64 v[4:5], 10, v[4:5]
	v_lshl_add_u64 v[4:5], v[4:5], 0, v[20:21]
	v_lshlrev_b64 v[4:5], 2, v[4:5]
	v_lshl_add_u64 v[6:7], s[12:13], 0, v[4:5]
	global_load_dword v6, v[6:7], off
	s_nop 0
	global_load_dword v7, v[0:1], off
	v_lshl_add_u64 v[4:5], s[10:11], 0, v[4:5]
	v_or_b32_e32 v12, 10, v2
	v_ashrrev_i32_e32 v13, 31, v12
	v_lshlrev_b64 v[12:13], 10, v[12:13]
	v_lshl_add_u64 v[12:13], v[12:13], 0, v[20:21]
	v_lshlrev_b64 v[12:13], 2, v[12:13]
	v_lshl_add_u64 v[14:15], s[12:13], 0, v[12:13]
	v_lshl_add_u64 v[12:13], s[10:11], 0, v[12:13]
	s_waitcnt vmcnt(0)
	v_mul_f32_e32 v7, 0.5, v7
	v_fmac_f32_e32 v6, v3, v7
	global_store_dword v[4:5], v6, off
	ds_read2st64_b32 v[4:5], v27 offset0:6 offset1:7
	ds_read2st64_b32 v[6:7], v27 offset0:22 offset1:23
	ds_read2st64_b32 v[8:9], v27 offset0:38 offset1:39
	ds_read2st64_b32 v[10:11], v27 offset0:54 offset1:55
	s_waitcnt lgkmcnt(2)
	v_add_f32_e32 v3, v4, v6
	s_waitcnt lgkmcnt(0)
	v_add_f32_e32 v4, v8, v10
	v_add_f32_e32 v3, v3, v4
	global_load_dword v4, v[14:15], off
	global_load_dword v6, v[0:1], off
	s_waitcnt vmcnt(0)
	v_mul_f32_e32 v6, 0.5, v6
	v_fmac_f32_e32 v4, v3, v6
	global_store_dword v[12:13], v4, off
	v_add_f32_e32 v3, v5, v7
	v_add_f32_e32 v4, v9, v11
	v_add_f32_e32 v3, v3, v4
	v_or_b32_e32 v4, 11, v2
	v_ashrrev_i32_e32 v5, 31, v4
	v_lshlrev_b64 v[4:5], 10, v[4:5]
	v_lshl_add_u64 v[4:5], v[4:5], 0, v[20:21]
	v_lshlrev_b64 v[4:5], 2, v[4:5]
	v_lshl_add_u64 v[6:7], s[12:13], 0, v[4:5]
	global_load_dword v6, v[6:7], off
	s_nop 0
	global_load_dword v7, v[0:1], off
	v_lshl_add_u64 v[4:5], s[10:11], 0, v[4:5]
	v_or_b32_e32 v12, 16, v2
	v_ashrrev_i32_e32 v13, 31, v12
	v_lshlrev_b64 v[12:13], 10, v[12:13]
	v_lshl_add_u64 v[12:13], v[12:13], 0, v[20:21]
	v_lshlrev_b64 v[12:13], 2, v[12:13]
	v_lshl_add_u64 v[14:15], s[12:13], 0, v[12:13]
	v_lshl_add_u64 v[12:13], s[10:11], 0, v[12:13]
	s_waitcnt vmcnt(0)
	v_mul_f32_e32 v7, 0.5, v7
	v_fmac_f32_e32 v6, v3, v7
	global_store_dword v[4:5], v6, off
	ds_read2st64_b32 v[4:5], v27 offset0:8 offset1:9
	ds_read2st64_b32 v[6:7], v27 offset0:24 offset1:25
	ds_read2st64_b32 v[8:9], v27 offset0:40 offset1:41
	ds_read2st64_b32 v[10:11], v27 offset0:56 offset1:57
	s_waitcnt lgkmcnt(2)
	v_add_f32_e32 v3, v4, v6
	s_waitcnt lgkmcnt(0)
	v_add_f32_e32 v4, v8, v10
	v_add_f32_e32 v3, v3, v4
	global_load_dword v4, v[14:15], off
	global_load_dword v6, v[0:1], off
	s_waitcnt vmcnt(0)
	v_mul_f32_e32 v6, 0.5, v6
	v_fmac_f32_e32 v4, v3, v6
	global_store_dword v[12:13], v4, off
	v_add_f32_e32 v3, v5, v7
	v_add_f32_e32 v4, v9, v11
	v_add_f32_e32 v3, v3, v4
	v_or_b32_e32 v4, 17, v2
	v_ashrrev_i32_e32 v5, 31, v4
	v_lshlrev_b64 v[4:5], 10, v[4:5]
	v_lshl_add_u64 v[4:5], v[4:5], 0, v[20:21]
	v_lshlrev_b64 v[4:5], 2, v[4:5]
	v_lshl_add_u64 v[6:7], s[12:13], 0, v[4:5]
	global_load_dword v6, v[6:7], off
	s_nop 0
	global_load_dword v7, v[0:1], off
	v_lshl_add_u64 v[4:5], s[10:11], 0, v[4:5]
	v_or_b32_e32 v12, 18, v2
	v_ashrrev_i32_e32 v13, 31, v12
	v_lshlrev_b64 v[12:13], 10, v[12:13]
	v_lshl_add_u64 v[12:13], v[12:13], 0, v[20:21]
	v_lshlrev_b64 v[12:13], 2, v[12:13]
	v_lshl_add_u64 v[14:15], s[12:13], 0, v[12:13]
	v_lshl_add_u64 v[12:13], s[10:11], 0, v[12:13]
	s_waitcnt vmcnt(0)
	v_mul_f32_e32 v7, 0.5, v7
	v_fmac_f32_e32 v6, v3, v7
	global_store_dword v[4:5], v6, off
	ds_read2st64_b32 v[4:5], v27 offset0:10 offset1:11
	ds_read2st64_b32 v[6:7], v27 offset0:26 offset1:27
	ds_read2st64_b32 v[8:9], v27 offset0:42 offset1:43
	ds_read2st64_b32 v[10:11], v27 offset0:58 offset1:59
	s_waitcnt lgkmcnt(2)
	v_add_f32_e32 v3, v4, v6
	s_waitcnt lgkmcnt(0)
	v_add_f32_e32 v4, v8, v10
	v_add_f32_e32 v3, v3, v4
	global_load_dword v4, v[14:15], off
	global_load_dword v6, v[0:1], off
	s_waitcnt vmcnt(0)
	v_mul_f32_e32 v6, 0.5, v6
	v_fmac_f32_e32 v4, v3, v6
	global_store_dword v[12:13], v4, off
	v_add_f32_e32 v3, v5, v7
	v_add_f32_e32 v4, v9, v11
	v_add_f32_e32 v3, v3, v4
	v_or_b32_e32 v4, 19, v2
	v_ashrrev_i32_e32 v5, 31, v4
	v_lshlrev_b64 v[4:5], 10, v[4:5]
	v_lshl_add_u64 v[4:5], v[4:5], 0, v[20:21]
	v_lshlrev_b64 v[4:5], 2, v[4:5]
	v_lshl_add_u64 v[6:7], s[12:13], 0, v[4:5]
	global_load_dword v6, v[6:7], off
	s_nop 0
	global_load_dword v7, v[0:1], off
	v_lshl_add_u64 v[4:5], s[10:11], 0, v[4:5]
	v_or_b32_e32 v12, 24, v2
	v_ashrrev_i32_e32 v13, 31, v12
	v_lshlrev_b64 v[12:13], 10, v[12:13]
	v_lshl_add_u64 v[12:13], v[12:13], 0, v[20:21]
	v_lshlrev_b64 v[12:13], 2, v[12:13]
	v_lshl_add_u64 v[14:15], s[12:13], 0, v[12:13]
	v_lshl_add_u64 v[12:13], s[10:11], 0, v[12:13]
	s_waitcnt vmcnt(0)
	v_mul_f32_e32 v7, 0.5, v7
	v_fmac_f32_e32 v6, v3, v7
	global_store_dword v[4:5], v6, off
	ds_read2st64_b32 v[4:5], v27 offset0:12 offset1:13
	ds_read2st64_b32 v[6:7], v27 offset0:28 offset1:29
	ds_read2st64_b32 v[8:9], v27 offset0:44 offset1:45
	ds_read2st64_b32 v[10:11], v27 offset0:60 offset1:61
	s_waitcnt lgkmcnt(2)
	v_add_f32_e32 v3, v4, v6
	s_waitcnt lgkmcnt(0)
	v_add_f32_e32 v4, v8, v10
	v_add_f32_e32 v3, v3, v4
	global_load_dword v4, v[14:15], off
	global_load_dword v6, v[0:1], off
	s_waitcnt vmcnt(0)
	v_mul_f32_e32 v6, 0.5, v6
	v_fmac_f32_e32 v4, v3, v6
	global_store_dword v[12:13], v4, off
	v_add_f32_e32 v3, v5, v7
	v_add_f32_e32 v4, v9, v11
	v_add_f32_e32 v3, v3, v4
	v_or_b32_e32 v4, 25, v2
	v_ashrrev_i32_e32 v5, 31, v4
	v_lshlrev_b64 v[4:5], 10, v[4:5]
	v_lshl_add_u64 v[4:5], v[4:5], 0, v[20:21]
	v_lshlrev_b64 v[4:5], 2, v[4:5]
	v_lshl_add_u64 v[6:7], s[12:13], 0, v[4:5]
	global_load_dword v6, v[6:7], off
	s_nop 0
	global_load_dword v7, v[0:1], off
	v_lshl_add_u64 v[4:5], s[10:11], 0, v[4:5]
	v_or_b32_e32 v12, 26, v2
	v_ashrrev_i32_e32 v13, 31, v12
	v_lshlrev_b64 v[12:13], 10, v[12:13]
	v_lshl_add_u64 v[12:13], v[12:13], 0, v[20:21]
	v_lshlrev_b64 v[12:13], 2, v[12:13]
	v_lshl_add_u64 v[14:15], s[12:13], 0, v[12:13]
	v_lshl_add_u64 v[12:13], s[10:11], 0, v[12:13]
	v_or_b32_e32 v2, 27, v2
	s_waitcnt vmcnt(0)
	v_mul_f32_e32 v7, 0.5, v7
	v_fmac_f32_e32 v6, v3, v7
	global_store_dword v[4:5], v6, off
	ds_read2st64_b32 v[4:5], v27 offset0:14 offset1:15
	ds_read2st64_b32 v[6:7], v27 offset0:30 offset1:31
	ds_read2st64_b32 v[8:9], v27 offset0:46 offset1:47
	ds_read2st64_b32 v[10:11], v27 offset0:62 offset1:63
	s_waitcnt lgkmcnt(2)
	v_add_f32_e32 v3, v4, v6
	s_waitcnt lgkmcnt(0)
	v_add_f32_e32 v4, v8, v10
	v_add_f32_e32 v3, v3, v4
	global_load_dword v4, v[14:15], off
	global_load_dword v6, v[0:1], off
	s_waitcnt vmcnt(0)
	v_mul_f32_e32 v6, 0.5, v6
	v_fmac_f32_e32 v4, v3, v6
	global_store_dword v[12:13], v4, off
	v_add_f32_e32 v3, v5, v7
	v_add_f32_e32 v4, v9, v11
	v_add_f32_e32 v6, v3, v4
	v_ashrrev_i32_e32 v3, 31, v2
	v_lshlrev_b64 v[2:3], 10, v[2:3]
	v_lshl_add_u64 v[2:3], v[2:3], 0, v[20:21]
	v_lshlrev_b64 v[2:3], 2, v[2:3]
	v_lshl_add_u64 v[4:5], s[12:13], 0, v[2:3]
	global_load_dword v4, v[4:5], off
	s_nop 0
	global_load_dword v0, v[0:1], off
	s_waitcnt vmcnt(0)
	v_mul_f32_e32 v0, 0.5, v0
	v_fmac_f32_e32 v4, v6, v0
	v_lshl_add_u64 v[0:1], s[10:11], 0, v[2:3]
	global_store_dword v[0:1], v4, off
	s_branch .LBB0_405

.LBB0_1005:
	global_load_dwordx4 v[40:43], v[24:25], off offset:-128
	global_load_dwordx4 v[44:47], v[22:23], off offset:-128
	global_load_dwordx4 v[48:51], v[24:25], off offset:-96
	global_load_dwordx4 v[52:55], v[22:23], off offset:-96
	global_load_dwordx4 v[56:59], v[24:25], off offset:-64
	global_load_dwordx4 v[60:63], v[22:23], off offset:-64
	global_load_dwordx4 v[64:67], v[24:25], off offset:-32
	global_load_dwordx4 v[68:71], v[22:23], off offset:-32
	global_load_dwordx4 v[72:75], v[24:25], off
	global_load_dwordx4 v[76:79], v[22:23], off
	global_load_dwordx4 v[80:83], v[24:25], off offset:32
	global_load_dwordx4 v[84:87], v[22:23], off offset:32
	global_load_dwordx4 v[88:91], v[24:25], off offset:64
	global_load_dwordx4 v[92:95], v[22:23], off offset:64
	global_load_dwordx4 v[96:99], v[24:25], off offset:96
	global_load_dwordx4 v[100:103], v[22:23], off offset:96
	s_addk_i32 s5, 0x80
	s_cmpk_gt_u32 s5, 0xef
	v_lshl_add_u64 v[22:23], v[22:23], 0, s[96:97]
	v_lshl_add_u64 v[24:25], v[24:25], 0, s[96:97]
	s_waitcnt vmcnt(14)
	v_mfma_f32_32x32x16_bf16 v[0:15], v[40:43], v[44:47], v[0:15]
	s_waitcnt vmcnt(12)
	v_mfma_f32_32x32x16_bf16 v[0:15], v[48:51], v[52:55], v[0:15]
	s_waitcnt vmcnt(10)
	v_mfma_f32_32x32x16_bf16 v[0:15], v[56:59], v[60:63], v[0:15]
	s_waitcnt vmcnt(8)
	v_mfma_f32_32x32x16_bf16 v[0:15], v[64:67], v[68:71], v[0:15]
	s_waitcnt vmcnt(6)
	v_mfma_f32_32x32x16_bf16 v[0:15], v[72:75], v[76:79], v[0:15]
	s_waitcnt vmcnt(4)
	v_mfma_f32_32x32x16_bf16 v[0:15], v[80:83], v[84:87], v[0:15]
	s_waitcnt vmcnt(2)
	v_mfma_f32_32x32x16_bf16 v[0:15], v[88:91], v[92:95], v[0:15]
	s_waitcnt vmcnt(0)
	v_mfma_f32_32x32x16_bf16 v[0:15], v[96:99], v[100:103], v[0:15]
	s_cbranch_scc0 .LBB0_1005
	s_and_b64 vcc, exec, s[38:39]
	s_nop 9
	ds_write2st64_b32 v27, v0, v1 offset1:1
	ds_write2st64_b32 v27, v2, v3 offset0:2 offset1:3
	ds_write2st64_b32 v27, v4, v5 offset0:4 offset1:5
	ds_write2st64_b32 v27, v6, v7 offset0:6 offset1:7
	ds_write2st64_b32 v27, v8, v9 offset0:8 offset1:9
	ds_write2st64_b32 v27, v10, v11 offset0:10 offset1:11
	ds_write2st64_b32 v27, v12, v13 offset0:12 offset1:13
	ds_write2st64_b32 v27, v14, v15 offset0:14 offset1:15
	s_waitcnt lgkmcnt(0)
	s_barrier
	s_cbranch_vccz .LBB0_1003
	v_lshl_add_u64 v[0:1], v[20:21], 2, s[10:11]
	global_load_dword v12, v[0:1], off
	ds_read2st64_b32 v[4:5], v27 offset1:1
	ds_read2st64_b32 v[6:7], v27 offset0:16 offset1:17
	ds_read2st64_b32 v[8:9], v27 offset0:32 offset1:33
	ds_read2st64_b32 v[10:11], v27 offset0:48 offset1:49
	v_or_b32_e32 v2, s4, v28
	v_lshl_add_u64 v[0:1], v[20:21], 1, s[36:37]
	s_waitcnt lgkmcnt(2)
	v_add_f32_e32 v3, v4, v6
	s_waitcnt lgkmcnt(0)
	v_add_f32_e32 v4, v8, v10
	v_add_f32_e32 v3, v3, v4
	s_waitcnt vmcnt(0)
	v_add_f32_e32 v3, v12, v3
	v_mul_f32_e32 v3, 0xbfb8aa3b, v3
	v_exp_f32_e32 v3, v3
	s_nop 0
	v_add_f32_e32 v3, 1.0, v3
	v_div_scale_f32 v4, s[4:5], v3, v3, 1.0
	v_rcp_f32_e32 v6, v4
	s_nop 0
	v_fma_f32 v8, -v4, v6, 1.0
	v_fmac_f32_e32 v6, v8, v6
	v_div_scale_f32 v8, vcc, 1.0, v3, 1.0
	v_mul_f32_e32 v10, v8, v6
	v_fma_f32 v13, -v4, v10, v8
	v_fmac_f32_e32 v10, v13, v6
	v_fma_f32 v4, -v4, v10, v8
	v_div_fmas_f32 v4, v4, v6, v10
	v_div_fixup_f32 v3, v4, v3, 1.0
	v_bfe_u32 v4, v3, 16, 1
	v_add3_u32 v4, v3, v4, s94
	v_ashrrev_i32_e32 v3, 31, v2
	v_lshlrev_b64 v[14:15], 12, v[2:3]
	v_lshl_add_u64 v[14:15], v[0:1], 0, v[14:15]
	global_store_short_d16_hi v[14:15], v4, off
	v_add_f32_e32 v3, v5, v7
	v_add_f32_e32 v4, v9, v11
	v_add_f32_e32 v3, v3, v4
	v_add_f32_e32 v3, v12, v3
	v_mul_f32_e32 v3, 0xbfb8aa3b, v3
	v_exp_f32_e32 v3, v3
	v_or_b32_e32 v4, 1, v2
	v_or_b32_e32 v14, 2, v2
	v_ashrrev_i32_e32 v15, 31, v14
	v_add_f32_e32 v3, 1.0, v3
	v_div_scale_f32 v5, s[4:5], v3, v3, 1.0
	v_rcp_f32_e32 v6, v5
	v_lshlrev_b64 v[14:15], 12, v[14:15]
	v_lshl_add_u64 v[14:15], v[0:1], 0, v[14:15]
	v_fma_f32 v7, -v5, v6, 1.0
	v_fmac_f32_e32 v6, v7, v6
	v_div_scale_f32 v7, vcc, 1.0, v3, 1.0
	v_mul_f32_e32 v8, v7, v6
	v_fma_f32 v9, -v5, v8, v7
	v_fmac_f32_e32 v8, v9, v6
	v_fma_f32 v5, -v5, v8, v7
	v_div_fmas_f32 v5, v5, v6, v8
	v_div_fixup_f32 v3, v5, v3, 1.0
	v_bfe_u32 v5, v3, 16, 1
	v_add3_u32 v3, v3, v5, s94
	v_ashrrev_i32_e32 v5, 31, v4
	v_lshlrev_b64 v[4:5], 12, v[4:5]
	v_lshl_add_u64 v[4:5], v[0:1], 0, v[4:5]
	global_store_short_d16_hi v[4:5], v3, off
	ds_read2st64_b32 v[4:5], v27 offset0:2 offset1:3
	ds_read2st64_b32 v[6:7], v27 offset0:18 offset1:19
	ds_read2st64_b32 v[8:9], v27 offset0:34 offset1:35
	ds_read2st64_b32 v[10:11], v27 offset0:50 offset1:51
	s_waitcnt lgkmcnt(2)
	v_add_f32_e32 v3, v4, v6
	s_waitcnt lgkmcnt(0)
	v_add_f32_e32 v4, v8, v10
	v_add_f32_e32 v3, v3, v4
	v_add_f32_e32 v3, v12, v3
	v_mul_f32_e32 v3, 0xbfb8aa3b, v3
	v_exp_f32_e32 v3, v3
	s_nop 0
	v_add_f32_e32 v3, 1.0, v3
	v_div_scale_f32 v4, s[4:5], v3, v3, 1.0
	v_rcp_f32_e32 v6, v4
	s_nop 0
	v_fma_f32 v8, -v4, v6, 1.0
	v_fmac_f32_e32 v6, v8, v6
	v_div_scale_f32 v8, vcc, 1.0, v3, 1.0
	v_mul_f32_e32 v10, v8, v6
	v_fma_f32 v13, -v4, v10, v8
	v_fmac_f32_e32 v10, v13, v6
	v_fma_f32 v4, -v4, v10, v8
	v_div_fmas_f32 v4, v4, v6, v10
	v_div_fixup_f32 v3, v4, v3, 1.0
	v_bfe_u32 v4, v3, 16, 1
	v_add3_u32 v3, v3, v4, s94
	global_store_short_d16_hi v[14:15], v3, off
	v_add_f32_e32 v3, v5, v7
	v_add_f32_e32 v4, v9, v11
	v_add_f32_e32 v3, v3, v4
	v_add_f32_e32 v3, v12, v3
	v_mul_f32_e32 v3, 0xbfb8aa3b, v3
	v_exp_f32_e32 v3, v3
	v_or_b32_e32 v4, 3, v2
	v_or_b32_e32 v14, 8, v2
	v_ashrrev_i32_e32 v15, 31, v14
	v_add_f32_e32 v3, 1.0, v3
	v_div_scale_f32 v5, s[4:5], v3, v3, 1.0
	v_rcp_f32_e32 v6, v5
	v_lshlrev_b64 v[14:15], 12, v[14:15]
	v_lshl_add_u64 v[14:15], v[0:1], 0, v[14:15]
	v_fma_f32 v7, -v5, v6, 1.0
	v_fmac_f32_e32 v6, v7, v6
	v_div_scale_f32 v7, vcc, 1.0, v3, 1.0
	v_mul_f32_e32 v8, v7, v6
	v_fma_f32 v9, -v5, v8, v7
	v_fmac_f32_e32 v8, v9, v6
	v_fma_f32 v5, -v5, v8, v7
	v_div_fmas_f32 v5, v5, v6, v8
	v_div_fixup_f32 v3, v5, v3, 1.0
	v_bfe_u32 v5, v3, 16, 1
	v_add3_u32 v3, v3, v5, s94
	v_ashrrev_i32_e32 v5, 31, v4
	v_lshlrev_b64 v[4:5], 12, v[4:5]
	v_lshl_add_u64 v[4:5], v[0:1], 0, v[4:5]
	global_store_short_d16_hi v[4:5], v3, off
	ds_read2st64_b32 v[4:5], v27 offset0:4 offset1:5
	ds_read2st64_b32 v[6:7], v27 offset0:20 offset1:21
	ds_read2st64_b32 v[8:9], v27 offset0:36 offset1:37
	ds_read2st64_b32 v[10:11], v27 offset0:52 offset1:53
	s_waitcnt lgkmcnt(2)
	v_add_f32_e32 v3, v4, v6
	s_waitcnt lgkmcnt(0)
	v_add_f32_e32 v4, v8, v10
	v_add_f32_e32 v3, v3, v4
	v_add_f32_e32 v3, v12, v3
	v_mul_f32_e32 v3, 0xbfb8aa3b, v3
	v_exp_f32_e32 v3, v3
	s_nop 0
	v_add_f32_e32 v3, 1.0, v3
	v_div_scale_f32 v4, s[4:5], v3, v3, 1.0
	v_rcp_f32_e32 v6, v4
	s_nop 0
	v_fma_f32 v8, -v4, v6, 1.0
	v_fmac_f32_e32 v6, v8, v6
	v_div_scale_f32 v8, vcc, 1.0, v3, 1.0
	v_mul_f32_e32 v10, v8, v6
	v_fma_f32 v13, -v4, v10, v8
	v_fmac_f32_e32 v10, v13, v6
	v_fma_f32 v4, -v4, v10, v8
	v_div_fmas_f32 v4, v4, v6, v10
	v_div_fixup_f32 v3, v4, v3, 1.0
	v_bfe_u32 v4, v3, 16, 1
	v_add3_u32 v3, v3, v4, s94
	global_store_short_d16_hi v[14:15], v3, off
	v_add_f32_e32 v3, v5, v7
	v_add_f32_e32 v4, v9, v11
	v_add_f32_e32 v3, v3, v4
	v_add_f32_e32 v3, v12, v3
	v_mul_f32_e32 v3, 0xbfb8aa3b, v3
	v_exp_f32_e32 v3, v3
	v_or_b32_e32 v4, 9, v2
	v_or_b32_e32 v14, 10, v2
	v_ashrrev_i32_e32 v15, 31, v14
	v_add_f32_e32 v3, 1.0, v3
	v_div_scale_f32 v5, s[4:5], v3, v3, 1.0
	v_rcp_f32_e32 v6, v5
	v_lshlrev_b64 v[14:15], 12, v[14:15]
	v_lshl_add_u64 v[14:15], v[0:1], 0, v[14:15]
	v_fma_f32 v7, -v5, v6, 1.0
	v_fmac_f32_e32 v6, v7, v6
	v_div_scale_f32 v7, vcc, 1.0, v3, 1.0
	v_mul_f32_e32 v8, v7, v6
	v_fma_f32 v9, -v5, v8, v7
	v_fmac_f32_e32 v8, v9, v6
	v_fma_f32 v5, -v5, v8, v7
	v_div_fmas_f32 v5, v5, v6, v8
	v_div_fixup_f32 v3, v5, v3, 1.0
	v_bfe_u32 v5, v3, 16, 1
	v_add3_u32 v3, v3, v5, s94
	v_ashrrev_i32_e32 v5, 31, v4
	v_lshlrev_b64 v[4:5], 12, v[4:5]
	v_lshl_add_u64 v[4:5], v[0:1], 0, v[4:5]
	global_store_short_d16_hi v[4:5], v3, off
	ds_read2st64_b32 v[4:5], v27 offset0:6 offset1:7
	ds_read2st64_b32 v[6:7], v27 offset0:22 offset1:23
	ds_read2st64_b32 v[8:9], v27 offset0:38 offset1:39
	ds_read2st64_b32 v[10:11], v27 offset0:54 offset1:55
	s_waitcnt lgkmcnt(2)
	v_add_f32_e32 v3, v4, v6
	s_waitcnt lgkmcnt(0)
	v_add_f32_e32 v4, v8, v10
	v_add_f32_e32 v3, v3, v4
	v_add_f32_e32 v3, v12, v3
	v_mul_f32_e32 v3, 0xbfb8aa3b, v3
	v_exp_f32_e32 v3, v3
	s_nop 0
	v_add_f32_e32 v3, 1.0, v3
	v_div_scale_f32 v4, s[4:5], v3, v3, 1.0
	v_rcp_f32_e32 v6, v4
	s_nop 0
	v_fma_f32 v8, -v4, v6, 1.0
	v_fmac_f32_e32 v6, v8, v6
	v_div_scale_f32 v8, vcc, 1.0, v3, 1.0
	v_mul_f32_e32 v10, v8, v6
	v_fma_f32 v13, -v4, v10, v8
	v_fmac_f32_e32 v10, v13, v6
	v_fma_f32 v4, -v4, v10, v8
	v_div_fmas_f32 v4, v4, v6, v10
	v_div_fixup_f32 v3, v4, v3, 1.0
	v_bfe_u32 v4, v3, 16, 1
	v_add3_u32 v3, v3, v4, s94
	global_store_short_d16_hi v[14:15], v3, off
	v_add_f32_e32 v3, v5, v7
	v_add_f32_e32 v4, v9, v11
	v_add_f32_e32 v3, v3, v4
	v_add_f32_e32 v3, v12, v3
	v_mul_f32_e32 v3, 0xbfb8aa3b, v3
	v_exp_f32_e32 v3, v3
	v_or_b32_e32 v4, 11, v2
	v_or_b32_e32 v14, 16, v2
	v_ashrrev_i32_e32 v15, 31, v14
	v_add_f32_e32 v3, 1.0, v3
	v_div_scale_f32 v5, s[4:5], v3, v3, 1.0
	v_rcp_f32_e32 v6, v5
	v_lshlrev_b64 v[14:15], 12, v[14:15]
	v_lshl_add_u64 v[14:15], v[0:1], 0, v[14:15]
	v_fma_f32 v7, -v5, v6, 1.0
	v_fmac_f32_e32 v6, v7, v6
	v_div_scale_f32 v7, vcc, 1.0, v3, 1.0
	v_mul_f32_e32 v8, v7, v6
	v_fma_f32 v9, -v5, v8, v7
	v_fmac_f32_e32 v8, v9, v6
	v_fma_f32 v5, -v5, v8, v7
	v_div_fmas_f32 v5, v5, v6, v8
	v_div_fixup_f32 v3, v5, v3, 1.0
	v_bfe_u32 v5, v3, 16, 1
	v_add3_u32 v3, v3, v5, s94
	v_ashrrev_i32_e32 v5, 31, v4
	v_lshlrev_b64 v[4:5], 12, v[4:5]
	v_lshl_add_u64 v[4:5], v[0:1], 0, v[4:5]
	global_store_short_d16_hi v[4:5], v3, off
	ds_read2st64_b32 v[4:5], v27 offset0:8 offset1:9
	ds_read2st64_b32 v[6:7], v27 offset0:24 offset1:25
	ds_read2st64_b32 v[8:9], v27 offset0:40 offset1:41
	ds_read2st64_b32 v[10:11], v27 offset0:56 offset1:57
	s_waitcnt lgkmcnt(2)
	v_add_f32_e32 v3, v4, v6
	s_waitcnt lgkmcnt(0)
	v_add_f32_e32 v4, v8, v10
	v_add_f32_e32 v3, v3, v4
	v_add_f32_e32 v3, v12, v3
	v_mul_f32_e32 v3, 0xbfb8aa3b, v3
	v_exp_f32_e32 v3, v3
	s_nop 0
	v_add_f32_e32 v3, 1.0, v3
	v_div_scale_f32 v4, s[4:5], v3, v3, 1.0
	v_rcp_f32_e32 v6, v4
	s_nop 0
	v_fma_f32 v8, -v4, v6, 1.0
	v_fmac_f32_e32 v6, v8, v6
	v_div_scale_f32 v8, vcc, 1.0, v3, 1.0
	v_mul_f32_e32 v10, v8, v6
	v_fma_f32 v13, -v4, v10, v8
	v_fmac_f32_e32 v10, v13, v6
	v_fma_f32 v4, -v4, v10, v8
	v_div_fmas_f32 v4, v4, v6, v10
	v_div_fixup_f32 v3, v4, v3, 1.0
	v_bfe_u32 v4, v3, 16, 1
	v_add3_u32 v3, v3, v4, s94
	global_store_short_d16_hi v[14:15], v3, off
	v_add_f32_e32 v3, v5, v7
	v_add_f32_e32 v4, v9, v11
	v_add_f32_e32 v3, v3, v4
	v_add_f32_e32 v3, v12, v3
	v_mul_f32_e32 v3, 0xbfb8aa3b, v3
	v_exp_f32_e32 v3, v3
	v_or_b32_e32 v4, 17, v2
	v_or_b32_e32 v14, 18, v2
	v_ashrrev_i32_e32 v15, 31, v14
	v_add_f32_e32 v3, 1.0, v3
	v_div_scale_f32 v5, s[4:5], v3, v3, 1.0
	v_rcp_f32_e32 v6, v5
	v_lshlrev_b64 v[14:15], 12, v[14:15]
	v_lshl_add_u64 v[14:15], v[0:1], 0, v[14:15]
	v_fma_f32 v7, -v5, v6, 1.0
	v_fmac_f32_e32 v6, v7, v6
	v_div_scale_f32 v7, vcc, 1.0, v3, 1.0
	v_mul_f32_e32 v8, v7, v6
	v_fma_f32 v9, -v5, v8, v7
	v_fmac_f32_e32 v8, v9, v6
	v_fma_f32 v5, -v5, v8, v7
	v_div_fmas_f32 v5, v5, v6, v8
	v_div_fixup_f32 v3, v5, v3, 1.0
	v_bfe_u32 v5, v3, 16, 1
	v_add3_u32 v3, v3, v5, s94
	v_ashrrev_i32_e32 v5, 31, v4
	v_lshlrev_b64 v[4:5], 12, v[4:5]
	v_lshl_add_u64 v[4:5], v[0:1], 0, v[4:5]
	global_store_short_d16_hi v[4:5], v3, off
	ds_read2st64_b32 v[4:5], v27 offset0:10 offset1:11
	ds_read2st64_b32 v[6:7], v27 offset0:26 offset1:27
	ds_read2st64_b32 v[8:9], v27 offset0:42 offset1:43
	ds_read2st64_b32 v[10:11], v27 offset0:58 offset1:59
	s_waitcnt lgkmcnt(2)
	v_add_f32_e32 v3, v4, v6
	s_waitcnt lgkmcnt(0)
	v_add_f32_e32 v4, v8, v10
	v_add_f32_e32 v3, v3, v4
	v_add_f32_e32 v3, v12, v3
	v_mul_f32_e32 v3, 0xbfb8aa3b, v3
	v_exp_f32_e32 v3, v3
	s_nop 0
	v_add_f32_e32 v3, 1.0, v3
	v_div_scale_f32 v4, s[4:5], v3, v3, 1.0
	v_rcp_f32_e32 v6, v4
	s_nop 0
	v_fma_f32 v8, -v4, v6, 1.0
	v_fmac_f32_e32 v6, v8, v6
	v_div_scale_f32 v8, vcc, 1.0, v3, 1.0
	v_mul_f32_e32 v10, v8, v6
	v_fma_f32 v13, -v4, v10, v8
	v_fmac_f32_e32 v10, v13, v6
	v_fma_f32 v4, -v4, v10, v8
	v_div_fmas_f32 v4, v4, v6, v10
	v_div_fixup_f32 v3, v4, v3, 1.0
	v_bfe_u32 v4, v3, 16, 1
	v_add3_u32 v3, v3, v4, s94
	global_store_short_d16_hi v[14:15], v3, off
	v_add_f32_e32 v3, v5, v7
	v_add_f32_e32 v4, v9, v11
	v_add_f32_e32 v3, v3, v4
	v_add_f32_e32 v3, v12, v3
	v_mul_f32_e32 v3, 0xbfb8aa3b, v3
	v_exp_f32_e32 v3, v3
	v_or_b32_e32 v4, 19, v2
	v_or_b32_e32 v14, 24, v2
	v_ashrrev_i32_e32 v15, 31, v14
	v_add_f32_e32 v3, 1.0, v3
	v_div_scale_f32 v5, s[4:5], v3, v3, 1.0
	v_rcp_f32_e32 v6, v5
	v_lshlrev_b64 v[14:15], 12, v[14:15]
	v_lshl_add_u64 v[14:15], v[0:1], 0, v[14:15]
	v_fma_f32 v7, -v5, v6, 1.0
	v_fmac_f32_e32 v6, v7, v6
	v_div_scale_f32 v7, vcc, 1.0, v3, 1.0
	v_mul_f32_e32 v8, v7, v6
	v_fma_f32 v9, -v5, v8, v7
	v_fmac_f32_e32 v8, v9, v6
	v_fma_f32 v5, -v5, v8, v7
	v_div_fmas_f32 v5, v5, v6, v8
	v_div_fixup_f32 v3, v5, v3, 1.0
	v_bfe_u32 v5, v3, 16, 1
	v_add3_u32 v3, v3, v5, s94
	v_ashrrev_i32_e32 v5, 31, v4
	v_lshlrev_b64 v[4:5], 12, v[4:5]
	v_lshl_add_u64 v[4:5], v[0:1], 0, v[4:5]
	global_store_short_d16_hi v[4:5], v3, off
	ds_read2st64_b32 v[4:5], v27 offset0:12 offset1:13
	ds_read2st64_b32 v[6:7], v27 offset0:28 offset1:29
	ds_read2st64_b32 v[8:9], v27 offset0:44 offset1:45
	ds_read2st64_b32 v[10:11], v27 offset0:60 offset1:61
	s_waitcnt lgkmcnt(2)
	v_add_f32_e32 v3, v4, v6
	s_waitcnt lgkmcnt(0)
	v_add_f32_e32 v4, v8, v10
	v_add_f32_e32 v3, v3, v4
	v_add_f32_e32 v3, v12, v3
	v_mul_f32_e32 v3, 0xbfb8aa3b, v3
	v_exp_f32_e32 v3, v3
	s_nop 0
	v_add_f32_e32 v3, 1.0, v3
	v_div_scale_f32 v4, s[4:5], v3, v3, 1.0
	v_rcp_f32_e32 v6, v4
	s_nop 0
	v_fma_f32 v8, -v4, v6, 1.0
	v_fmac_f32_e32 v6, v8, v6
	v_div_scale_f32 v8, vcc, 1.0, v3, 1.0
	v_mul_f32_e32 v10, v8, v6
	v_fma_f32 v13, -v4, v10, v8
	v_fmac_f32_e32 v10, v13, v6
	v_fma_f32 v4, -v4, v10, v8
	v_div_fmas_f32 v4, v4, v6, v10
	v_div_fixup_f32 v3, v4, v3, 1.0
	v_bfe_u32 v4, v3, 16, 1
	v_add3_u32 v3, v3, v4, s94
	global_store_short_d16_hi v[14:15], v3, off
	v_add_f32_e32 v3, v5, v7
	v_add_f32_e32 v4, v9, v11
	v_add_f32_e32 v3, v3, v4
	v_add_f32_e32 v3, v12, v3
	v_mul_f32_e32 v3, 0xbfb8aa3b, v3
	v_exp_f32_e32 v3, v3
	v_or_b32_e32 v4, 25, v2
	v_or_b32_e32 v14, 26, v2
	v_ashrrev_i32_e32 v15, 31, v14
	v_add_f32_e32 v3, 1.0, v3
	v_div_scale_f32 v5, s[4:5], v3, v3, 1.0
	v_rcp_f32_e32 v6, v5
	v_lshlrev_b64 v[14:15], 12, v[14:15]
	v_lshl_add_u64 v[14:15], v[0:1], 0, v[14:15]
	v_or_b32_e32 v2, 27, v2
	v_fma_f32 v7, -v5, v6, 1.0
	v_fmac_f32_e32 v6, v7, v6
	v_div_scale_f32 v7, vcc, 1.0, v3, 1.0
	v_mul_f32_e32 v8, v7, v6
	v_fma_f32 v9, -v5, v8, v7
	v_fmac_f32_e32 v8, v9, v6
	v_fma_f32 v5, -v5, v8, v7
	v_div_fmas_f32 v5, v5, v6, v8
	v_div_fixup_f32 v3, v5, v3, 1.0
	v_bfe_u32 v5, v3, 16, 1
	v_add3_u32 v3, v3, v5, s94
	v_ashrrev_i32_e32 v5, 31, v4
	v_lshlrev_b64 v[4:5], 12, v[4:5]
	v_lshl_add_u64 v[4:5], v[0:1], 0, v[4:5]
	global_store_short_d16_hi v[4:5], v3, off
	ds_read2st64_b32 v[4:5], v27 offset0:14 offset1:15
	ds_read2st64_b32 v[6:7], v27 offset0:30 offset1:31
	ds_read2st64_b32 v[8:9], v27 offset0:46 offset1:47
	ds_read2st64_b32 v[10:11], v27 offset0:62 offset1:63
	s_waitcnt lgkmcnt(2)
	v_add_f32_e32 v3, v4, v6
	s_waitcnt lgkmcnt(0)
	v_add_f32_e32 v4, v8, v10
	v_add_f32_e32 v3, v3, v4
	v_add_f32_e32 v3, v12, v3
	v_mul_f32_e32 v3, 0xbfb8aa3b, v3
	v_exp_f32_e32 v3, v3
	s_nop 0
	v_add_f32_e32 v3, 1.0, v3
	v_div_scale_f32 v4, s[4:5], v3, v3, 1.0
	v_rcp_f32_e32 v6, v4
	s_nop 0
	v_fma_f32 v8, -v4, v6, 1.0
	v_fmac_f32_e32 v6, v8, v6
	v_div_scale_f32 v8, vcc, 1.0, v3, 1.0
	v_mul_f32_e32 v10, v8, v6
	v_fma_f32 v13, -v4, v10, v8
	v_fmac_f32_e32 v10, v13, v6
	v_fma_f32 v4, -v4, v10, v8
	v_div_fmas_f32 v4, v4, v6, v10
	v_div_fixup_f32 v3, v4, v3, 1.0
	v_bfe_u32 v4, v3, 16, 1
	v_add3_u32 v3, v3, v4, s94
	global_store_short_d16_hi v[14:15], v3, off
	v_add_f32_e32 v3, v5, v7
	v_add_f32_e32 v4, v9, v11
	v_add_f32_e32 v3, v3, v4
	v_add_f32_e32 v3, v12, v3
	v_mul_f32_e32 v3, 0xbfb8aa3b, v3
	v_exp_f32_e32 v3, v3
	s_nop 0
	v_add_f32_e32 v3, 1.0, v3
	v_div_scale_f32 v4, s[4:5], v3, v3, 1.0
	v_rcp_f32_e32 v5, v4
	s_nop 0
	v_fma_f32 v6, -v4, v5, 1.0
	v_fmac_f32_e32 v5, v6, v5
	v_div_scale_f32 v6, vcc, 1.0, v3, 1.0
	v_mul_f32_e32 v7, v6, v5
	v_fma_f32 v8, -v4, v7, v6
	v_fmac_f32_e32 v7, v8, v5
	v_fma_f32 v4, -v4, v7, v6
	v_div_fmas_f32 v4, v4, v5, v7
	v_div_fixup_f32 v3, v4, v3, 1.0
	v_bfe_u32 v4, v3, 16, 1
	v_add3_u32 v4, v3, v4, s94
	v_ashrrev_i32_e32 v3, 31, v2
	v_lshlrev_b64 v[2:3], 12, v[2:3]
	v_lshl_add_u64 v[0:1], v[0:1], 0, v[2:3]
	global_store_short_d16_hi v[0:1], v4, off
	s_branch .LBB0_1003

.LBB0_1165:
	s_ashr_i32 s8, s4, 31
	s_lshr_b32 s8, s8, 27
	s_add_i32 s8, s4, s8
	s_and_b32 s9, s8, 0xffffffe0
	s_sub_i32 s10, s4, s9
	v_or_b32_e32 v0, s9, v24
	v_ashrrev_i32_e32 v1, 31, v0
	v_lshl_or_b32 v22, s10, 5, v24
	v_lshlrev_b64 v[0:1], 10, v[0:1]
	v_ashrrev_i32_e32 v23, 31, v22
	v_lshl_add_u64 v[36:37], v[16:17], 0, v[0:1]
	v_lshlrev_b64 v[0:1], 10, v[22:23]
	v_lshl_add_u64 v[38:39], v[18:19], 0, v[0:1]
	global_load_dwordx4 v[40:43], v[36:37], off
	global_load_dwordx4 v[44:47], v[38:39], off
	global_load_dwordx4 v[48:51], v[36:37], off offset:32
	global_load_dwordx4 v[52:55], v[38:39], off offset:32
	global_load_dwordx4 v[56:59], v[36:37], off offset:64
	global_load_dwordx4 v[60:63], v[38:39], off offset:64
	global_load_dwordx4 v[64:67], v[36:37], off offset:96
	global_load_dwordx4 v[68:71], v[38:39], off offset:96
	global_load_dwordx4 v[72:75], v[36:37], off offset:128
	global_load_dwordx4 v[76:79], v[38:39], off offset:128
	global_load_dwordx4 v[80:83], v[36:37], off offset:160
	global_load_dwordx4 v[84:87], v[38:39], off offset:160
	global_load_dwordx4 v[88:91], v[36:37], off offset:192
	global_load_dwordx4 v[92:95], v[38:39], off offset:192
	global_load_dwordx4 v[96:99], v[36:37], off offset:224
	global_load_dwordx4 v[100:103], v[38:39], off offset:224
	s_andn2_b64 vcc, exec, s[0:1]
	s_waitcnt vmcnt(14)
	v_mfma_f32_32x32x16_bf16 v[0:15], v[40:43], v[44:47], 0
	s_waitcnt vmcnt(12)
	v_mfma_f32_32x32x16_bf16 v[0:15], v[48:51], v[52:55], v[0:15]
	s_waitcnt vmcnt(10)
	v_mfma_f32_32x32x16_bf16 v[0:15], v[56:59], v[60:63], v[0:15]
	s_waitcnt vmcnt(8)
	v_mfma_f32_32x32x16_bf16 v[0:15], v[64:67], v[68:71], v[0:15]
	s_waitcnt vmcnt(6)
	v_mfma_f32_32x32x16_bf16 v[0:15], v[72:75], v[76:79], v[0:15]
	s_waitcnt vmcnt(4)
	v_mfma_f32_32x32x16_bf16 v[0:15], v[80:83], v[84:87], v[0:15]
	s_waitcnt vmcnt(2)
	v_mfma_f32_32x32x16_bf16 v[0:15], v[88:91], v[92:95], v[0:15]
	s_waitcnt vmcnt(0)
	v_mfma_f32_32x32x16_bf16 v[0:15], v[96:99], v[100:103], v[0:15]
	s_nop 11
	ds_write2st64_b32 v26, v0, v1 offset1:1
	ds_write2st64_b32 v26, v2, v3 offset0:2 offset1:3
	ds_write2st64_b32 v26, v4, v5 offset0:4 offset1:5
	ds_write2st64_b32 v26, v6, v7 offset0:6 offset1:7
	ds_write2st64_b32 v26, v8, v9 offset0:8 offset1:9
	ds_write2st64_b32 v26, v10, v11 offset0:10 offset1:11
	ds_write2st64_b32 v26, v12, v13 offset0:12 offset1:13
	ds_write2st64_b32 v26, v14, v15 offset0:14 offset1:15
	s_waitcnt lgkmcnt(0)
	s_barrier
	s_cbranch_vccnz .LBB0_1164
	ds_read2st64_b32 v[2:3], v26 offset1:1
	ds_read2st64_b32 v[4:5], v26 offset0:16 offset1:17
	ds_read2st64_b32 v[6:7], v26 offset0:32 offset1:33
	ds_read2st64_b32 v[8:9], v26 offset0:48 offset1:49
	v_ashrrev_i32_e32 v0, 1, v22
	s_ashr_i32 s8, s8, 5
	v_ashrrev_i32_e32 v1, 31, v0
	s_waitcnt lgkmcnt(2)
	v_add_f32_e32 v2, v2, v4
	s_waitcnt lgkmcnt(0)
	v_add_f32_e32 v4, v6, v8
	v_lshlrev_b64 v[0:1], 11, v[0:1]
	v_add_f32_e32 v2, v2, v4
	v_lshl_or_b32 v10, s8, 6, v25
	v_lshl_add_u64 v[0:1], v[20:21], 0, v[0:1]
	v_bfe_u32 v4, v2, 16, 1
	v_ashrrev_i32_e32 v11, 31, v10
	v_add3_u32 v2, v2, v4, s94
	v_lshl_add_u64 v[0:1], v[10:11], 1, v[0:1]
	global_store_short_d16_hi v[0:1], v2, off
	v_add_f32_e32 v2, v3, v5
	v_add_f32_e32 v3, v7, v9
	v_add_f32_e32 v2, v2, v3
	v_bfe_u32 v3, v2, 16, 1
	v_add3_u32 v2, v2, v3, s94
	global_store_short_d16_hi v[0:1], v2, off offset:4
	ds_read2st64_b32 v[2:3], v26 offset0:2 offset1:3
	ds_read2st64_b32 v[4:5], v26 offset0:18 offset1:19
	ds_read2st64_b32 v[6:7], v26 offset0:34 offset1:35
	ds_read2st64_b32 v[8:9], v26 offset0:50 offset1:51
	s_waitcnt lgkmcnt(2)
	v_add_f32_e32 v2, v2, v4
	s_waitcnt lgkmcnt(0)
	v_add_f32_e32 v4, v6, v8
	v_add_f32_e32 v2, v2, v4
	v_bfe_u32 v4, v2, 16, 1
	v_add3_u32 v2, v2, v4, s94
	global_store_short_d16_hi v[0:1], v2, off offset:8
	v_add_f32_e32 v2, v3, v5
	v_add_f32_e32 v3, v7, v9
	v_add_f32_e32 v2, v2, v3
	v_bfe_u32 v3, v2, 16, 1
	v_add3_u32 v2, v2, v3, s94
	global_store_short_d16_hi v[0:1], v2, off offset:12
	ds_read2st64_b32 v[2:3], v26 offset0:4 offset1:5
	ds_read2st64_b32 v[4:5], v26 offset0:20 offset1:21
	ds_read2st64_b32 v[6:7], v26 offset0:36 offset1:37
	ds_read2st64_b32 v[8:9], v26 offset0:52 offset1:53
	s_waitcnt lgkmcnt(2)
	v_add_f32_e32 v2, v2, v4
	s_waitcnt lgkmcnt(0)
	v_add_f32_e32 v4, v6, v8
	v_add_f32_e32 v2, v2, v4
	v_bfe_u32 v4, v2, 16, 1
	v_add3_u32 v2, v2, v4, s94
	global_store_short_d16_hi v[0:1], v2, off offset:32
	v_add_f32_e32 v2, v3, v5
	v_add_f32_e32 v3, v7, v9
	v_add_f32_e32 v2, v2, v3
	v_bfe_u32 v3, v2, 16, 1
	v_add3_u32 v2, v2, v3, s94
	global_store_short_d16_hi v[0:1], v2, off offset:36
	ds_read2st64_b32 v[2:3], v26 offset0:6 offset1:7
	ds_read2st64_b32 v[4:5], v26 offset0:22 offset1:23
	ds_read2st64_b32 v[6:7], v26 offset0:38 offset1:39
	ds_read2st64_b32 v[8:9], v26 offset0:54 offset1:55
	s_waitcnt lgkmcnt(2)
	v_add_f32_e32 v2, v2, v4
	s_waitcnt lgkmcnt(0)
	v_add_f32_e32 v4, v6, v8
	v_add_f32_e32 v2, v2, v4
	v_bfe_u32 v4, v2, 16, 1
	v_add3_u32 v2, v2, v4, s94
	global_store_short_d16_hi v[0:1], v2, off offset:40
	v_add_f32_e32 v2, v3, v5
	v_add_f32_e32 v3, v7, v9
	v_add_f32_e32 v2, v2, v3
	v_bfe_u32 v3, v2, 16, 1
	v_add3_u32 v2, v2, v3, s94
	global_store_short_d16_hi v[0:1], v2, off offset:44
	ds_read2st64_b32 v[2:3], v26 offset0:8 offset1:9
	ds_read2st64_b32 v[4:5], v26 offset0:24 offset1:25
	ds_read2st64_b32 v[6:7], v26 offset0:40 offset1:41
	ds_read2st64_b32 v[8:9], v26 offset0:56 offset1:57
	s_waitcnt lgkmcnt(2)
	v_add_f32_e32 v2, v2, v4
	s_waitcnt lgkmcnt(0)
	v_add_f32_e32 v4, v6, v8
	v_add_f32_e32 v2, v2, v4
	v_bfe_u32 v4, v2, 16, 1
	v_add3_u32 v2, v2, v4, s94
	global_store_short_d16_hi v[0:1], v2, off offset:64
	v_add_f32_e32 v2, v3, v5
	v_add_f32_e32 v3, v7, v9
	v_add_f32_e32 v2, v2, v3
	v_bfe_u32 v3, v2, 16, 1
	v_add3_u32 v2, v2, v3, s94
	global_store_short_d16_hi v[0:1], v2, off offset:68
	ds_read2st64_b32 v[2:3], v26 offset0:10 offset1:11
	ds_read2st64_b32 v[4:5], v26 offset0:26 offset1:27
	ds_read2st64_b32 v[6:7], v26 offset0:42 offset1:43
	ds_read2st64_b32 v[8:9], v26 offset0:58 offset1:59
	s_waitcnt lgkmcnt(2)
	v_add_f32_e32 v2, v2, v4
	s_waitcnt lgkmcnt(0)
	v_add_f32_e32 v4, v6, v8
	v_add_f32_e32 v2, v2, v4
	v_bfe_u32 v4, v2, 16, 1
	v_add3_u32 v2, v2, v4, s94
	global_store_short_d16_hi v[0:1], v2, off offset:72
	v_add_f32_e32 v2, v3, v5
	v_add_f32_e32 v3, v7, v9
	v_add_f32_e32 v2, v2, v3
	v_bfe_u32 v3, v2, 16, 1
	v_add3_u32 v2, v2, v3, s94
	global_store_short_d16_hi v[0:1], v2, off offset:76
	ds_read2st64_b32 v[2:3], v26 offset0:12 offset1:13
	ds_read2st64_b32 v[4:5], v26 offset0:28 offset1:29
	ds_read2st64_b32 v[6:7], v26 offset0:44 offset1:45
	ds_read2st64_b32 v[8:9], v26 offset0:60 offset1:61
	s_waitcnt lgkmcnt(2)
	v_add_f32_e32 v2, v2, v4
	s_waitcnt lgkmcnt(0)
	v_add_f32_e32 v4, v6, v8
	v_add_f32_e32 v2, v2, v4
	v_bfe_u32 v4, v2, 16, 1
	v_add3_u32 v2, v2, v4, s94
	global_store_short_d16_hi v[0:1], v2, off offset:96
	v_add_f32_e32 v2, v3, v5
	v_add_f32_e32 v3, v7, v9
	v_add_f32_e32 v2, v2, v3
	v_bfe_u32 v3, v2, 16, 1
	v_add3_u32 v2, v2, v3, s94
	global_store_short_d16_hi v[0:1], v2, off offset:100
	ds_read2st64_b32 v[2:3], v26 offset0:14 offset1:15
	ds_read2st64_b32 v[4:5], v26 offset0:30 offset1:31
	ds_read2st64_b32 v[6:7], v26 offset0:46 offset1:47
	ds_read2st64_b32 v[8:9], v26 offset0:62 offset1:63
	s_waitcnt lgkmcnt(2)
	v_add_f32_e32 v2, v2, v4
	s_waitcnt lgkmcnt(0)
	v_add_f32_e32 v4, v6, v8
	v_add_f32_e32 v2, v2, v4
	v_bfe_u32 v4, v2, 16, 1
	v_add3_u32 v2, v2, v4, s94
	global_store_short_d16_hi v[0:1], v2, off offset:104
	v_add_f32_e32 v2, v3, v5
	v_add_f32_e32 v3, v7, v9
	v_add_f32_e32 v2, v2, v3
	v_bfe_u32 v3, v2, 16, 1
	v_add3_u32 v2, v2, v3, s94
	global_store_short_d16_hi v[0:1], v2, off offset:108
	s_branch .LBB0_1164

.LBB0_1236:
	global_load_dwordx4 v[40:43], v[24:25], off offset:-128
	global_load_dwordx4 v[44:47], v[22:23], off offset:-128
	global_load_dwordx4 v[48:51], v[24:25], off offset:-96
	global_load_dwordx4 v[52:55], v[22:23], off offset:-96
	global_load_dwordx4 v[56:59], v[24:25], off offset:-64
	global_load_dwordx4 v[60:63], v[22:23], off offset:-64
	global_load_dwordx4 v[64:67], v[24:25], off offset:-32
	global_load_dwordx4 v[68:71], v[22:23], off offset:-32
	global_load_dwordx4 v[72:75], v[24:25], off
	global_load_dwordx4 v[76:79], v[22:23], off
	global_load_dwordx4 v[80:83], v[24:25], off offset:32
	global_load_dwordx4 v[84:87], v[22:23], off offset:32
	global_load_dwordx4 v[88:91], v[24:25], off offset:64
	global_load_dwordx4 v[92:95], v[22:23], off offset:64
	global_load_dwordx4 v[96:99], v[24:25], off offset:96
	global_load_dwordx4 v[100:103], v[22:23], off offset:96
	s_addk_i32 s9, 0x80
	s_cmpk_gt_u32 s9, 0xef
	v_lshl_add_u64 v[22:23], v[22:23], 0, s[96:97]
	v_lshl_add_u64 v[24:25], v[24:25], 0, s[96:97]
	s_waitcnt vmcnt(14)
	v_mfma_f32_32x32x16_bf16 v[0:15], v[40:43], v[44:47], v[0:15]
	s_waitcnt vmcnt(12)
	v_mfma_f32_32x32x16_bf16 v[0:15], v[48:51], v[52:55], v[0:15]
	s_waitcnt vmcnt(10)
	v_mfma_f32_32x32x16_bf16 v[0:15], v[56:59], v[60:63], v[0:15]
	s_waitcnt vmcnt(8)
	v_mfma_f32_32x32x16_bf16 v[0:15], v[64:67], v[68:71], v[0:15]
	s_waitcnt vmcnt(6)
	v_mfma_f32_32x32x16_bf16 v[0:15], v[72:75], v[76:79], v[0:15]
	s_waitcnt vmcnt(4)
	v_mfma_f32_32x32x16_bf16 v[0:15], v[80:83], v[84:87], v[0:15]
	s_waitcnt vmcnt(2)
	v_mfma_f32_32x32x16_bf16 v[0:15], v[88:91], v[92:95], v[0:15]
	s_waitcnt vmcnt(0)
	v_mfma_f32_32x32x16_bf16 v[0:15], v[96:99], v[100:103], v[0:15]
	s_cbranch_scc0 .LBB0_1236
	s_and_b64 vcc, exec, s[6:7]
	s_nop 9
	ds_write2st64_b32 v27, v0, v1 offset1:1
	ds_write2st64_b32 v27, v2, v3 offset0:2 offset1:3
	ds_write2st64_b32 v27, v4, v5 offset0:4 offset1:5
	ds_write2st64_b32 v27, v6, v7 offset0:6 offset1:7
	ds_write2st64_b32 v27, v8, v9 offset0:8 offset1:9
	ds_write2st64_b32 v27, v10, v11 offset0:10 offset1:11
	ds_write2st64_b32 v27, v12, v13 offset0:12 offset1:13
	ds_write2st64_b32 v27, v14, v15 offset0:14 offset1:15
	s_waitcnt lgkmcnt(0)
	s_barrier
	s_cbranch_vccz .LBB0_1234
	ds_read2st64_b32 v[4:5], v27 offset1:1
	ds_read2st64_b32 v[6:7], v27 offset0:16 offset1:17
	ds_read2st64_b32 v[8:9], v27 offset0:32 offset1:33
	ds_read2st64_b32 v[10:11], v27 offset0:48 offset1:49
	v_or_b32_e32 v2, s8, v28
	v_lshl_add_u64 v[0:1], v[20:21], 1, s[0:1]
	s_waitcnt lgkmcnt(2)
	v_add_f32_e32 v3, v4, v6
	s_waitcnt lgkmcnt(0)
	v_add_f32_e32 v4, v8, v10
	v_add_f32_e32 v3, v3, v4
	v_mul_f32_e32 v3, 0x3bb504f3, v3
	v_bfe_u32 v4, v3, 16, 1
	v_add3_u32 v4, v3, v4, s94
	v_ashrrev_i32_e32 v3, 31, v2
	v_lshlrev_b64 v[12:13], 10, v[2:3]
	v_lshl_add_u64 v[12:13], v[0:1], 0, v[12:13]
	global_store_short_d16_hi v[12:13], v4, off
	v_add_f32_e32 v3, v5, v7
	v_add_f32_e32 v4, v9, v11
	v_add_f32_e32 v3, v3, v4
	v_mul_f32_e32 v3, 0x3bb504f3, v3
	v_or_b32_e32 v4, 1, v2
	v_bfe_u32 v5, v3, 16, 1
	v_add3_u32 v3, v3, v5, s94
	v_ashrrev_i32_e32 v5, 31, v4
	v_lshlrev_b64 v[4:5], 10, v[4:5]
	v_lshl_add_u64 v[4:5], v[0:1], 0, v[4:5]
	global_store_short_d16_hi v[4:5], v3, off
	ds_read2st64_b32 v[4:5], v27 offset0:2 offset1:3
	ds_read2st64_b32 v[6:7], v27 offset0:18 offset1:19
	ds_read2st64_b32 v[8:9], v27 offset0:34 offset1:35
	ds_read2st64_b32 v[10:11], v27 offset0:50 offset1:51
	v_or_b32_e32 v12, 2, v2
	v_ashrrev_i32_e32 v13, 31, v12
	v_lshlrev_b64 v[12:13], 10, v[12:13]
	s_waitcnt lgkmcnt(2)
	v_add_f32_e32 v3, v4, v6
	s_waitcnt lgkmcnt(0)
	v_add_f32_e32 v4, v8, v10
	v_add_f32_e32 v3, v3, v4
	v_mul_f32_e32 v3, 0x3bb504f3, v3
	v_bfe_u32 v4, v3, 16, 1
	v_add3_u32 v3, v3, v4, s94
	v_lshl_add_u64 v[12:13], v[0:1], 0, v[12:13]
	global_store_short_d16_hi v[12:13], v3, off
	v_add_f32_e32 v3, v5, v7
	v_add_f32_e32 v4, v9, v11
	v_add_f32_e32 v3, v3, v4
	v_mul_f32_e32 v3, 0x3bb504f3, v3
	v_or_b32_e32 v4, 3, v2
	v_bfe_u32 v5, v3, 16, 1
	v_add3_u32 v3, v3, v5, s94
	v_ashrrev_i32_e32 v5, 31, v4
	v_lshlrev_b64 v[4:5], 10, v[4:5]
	v_lshl_add_u64 v[4:5], v[0:1], 0, v[4:5]
	global_store_short_d16_hi v[4:5], v3, off
	ds_read2st64_b32 v[4:5], v27 offset0:4 offset1:5
	ds_read2st64_b32 v[6:7], v27 offset0:20 offset1:21
	ds_read2st64_b32 v[8:9], v27 offset0:36 offset1:37
	ds_read2st64_b32 v[10:11], v27 offset0:52 offset1:53
	v_or_b32_e32 v12, 8, v2
	v_ashrrev_i32_e32 v13, 31, v12
	v_lshlrev_b64 v[12:13], 10, v[12:13]
	s_waitcnt lgkmcnt(2)
	v_add_f32_e32 v3, v4, v6
	s_waitcnt lgkmcnt(0)
	v_add_f32_e32 v4, v8, v10
	v_add_f32_e32 v3, v3, v4
	v_mul_f32_e32 v3, 0x3bb504f3, v3
	v_bfe_u32 v4, v3, 16, 1
	v_add3_u32 v3, v3, v4, s94
	v_lshl_add_u64 v[12:13], v[0:1], 0, v[12:13]
	global_store_short_d16_hi v[12:13], v3, off
	v_add_f32_e32 v3, v5, v7
	v_add_f32_e32 v4, v9, v11
	v_add_f32_e32 v3, v3, v4
	v_mul_f32_e32 v3, 0x3bb504f3, v3
	v_or_b32_e32 v4, 9, v2
	v_bfe_u32 v5, v3, 16, 1
	v_add3_u32 v3, v3, v5, s94
	v_ashrrev_i32_e32 v5, 31, v4
	v_lshlrev_b64 v[4:5], 10, v[4:5]
	v_lshl_add_u64 v[4:5], v[0:1], 0, v[4:5]
	global_store_short_d16_hi v[4:5], v3, off
	ds_read2st64_b32 v[4:5], v27 offset0:6 offset1:7
	ds_read2st64_b32 v[6:7], v27 offset0:22 offset1:23
	ds_read2st64_b32 v[8:9], v27 offset0:38 offset1:39
	ds_read2st64_b32 v[10:11], v27 offset0:54 offset1:55
	v_or_b32_e32 v12, 10, v2
	v_ashrrev_i32_e32 v13, 31, v12
	v_lshlrev_b64 v[12:13], 10, v[12:13]
	s_waitcnt lgkmcnt(2)
	v_add_f32_e32 v3, v4, v6
	s_waitcnt lgkmcnt(0)
	v_add_f32_e32 v4, v8, v10
	v_add_f32_e32 v3, v3, v4
	v_mul_f32_e32 v3, 0x3bb504f3, v3
	v_bfe_u32 v4, v3, 16, 1
	v_add3_u32 v3, v3, v4, s94
	v_lshl_add_u64 v[12:13], v[0:1], 0, v[12:13]
	global_store_short_d16_hi v[12:13], v3, off
	v_add_f32_e32 v3, v5, v7
	v_add_f32_e32 v4, v9, v11
	v_add_f32_e32 v3, v3, v4
	v_mul_f32_e32 v3, 0x3bb504f3, v3
	v_or_b32_e32 v4, 11, v2
	v_bfe_u32 v5, v3, 16, 1
	v_add3_u32 v3, v3, v5, s94
	v_ashrrev_i32_e32 v5, 31, v4
	v_lshlrev_b64 v[4:5], 10, v[4:5]
	v_lshl_add_u64 v[4:5], v[0:1], 0, v[4:5]
	global_store_short_d16_hi v[4:5], v3, off
	ds_read2st64_b32 v[4:5], v27 offset0:8 offset1:9
	ds_read2st64_b32 v[6:7], v27 offset0:24 offset1:25
	ds_read2st64_b32 v[8:9], v27 offset0:40 offset1:41
	ds_read2st64_b32 v[10:11], v27 offset0:56 offset1:57
	v_or_b32_e32 v12, 16, v2
	v_ashrrev_i32_e32 v13, 31, v12
	v_lshlrev_b64 v[12:13], 10, v[12:13]
	s_waitcnt lgkmcnt(2)
	v_add_f32_e32 v3, v4, v6
	s_waitcnt lgkmcnt(0)
	v_add_f32_e32 v4, v8, v10
	v_add_f32_e32 v3, v3, v4
	v_mul_f32_e32 v3, 0x3bb504f3, v3
	v_bfe_u32 v4, v3, 16, 1
	v_add3_u32 v3, v3, v4, s94
	v_lshl_add_u64 v[12:13], v[0:1], 0, v[12:13]
	global_store_short_d16_hi v[12:13], v3, off
	v_add_f32_e32 v3, v5, v7
	v_add_f32_e32 v4, v9, v11
	v_add_f32_e32 v3, v3, v4
	v_mul_f32_e32 v3, 0x3bb504f3, v3
	v_or_b32_e32 v4, 17, v2
	v_bfe_u32 v5, v3, 16, 1
	v_add3_u32 v3, v3, v5, s94
	v_ashrrev_i32_e32 v5, 31, v4
	v_lshlrev_b64 v[4:5], 10, v[4:5]
	v_lshl_add_u64 v[4:5], v[0:1], 0, v[4:5]
	global_store_short_d16_hi v[4:5], v3, off
	ds_read2st64_b32 v[4:5], v27 offset0:10 offset1:11
	ds_read2st64_b32 v[6:7], v27 offset0:26 offset1:27
	ds_read2st64_b32 v[8:9], v27 offset0:42 offset1:43
	ds_read2st64_b32 v[10:11], v27 offset0:58 offset1:59
	v_or_b32_e32 v12, 18, v2
	v_ashrrev_i32_e32 v13, 31, v12
	v_lshlrev_b64 v[12:13], 10, v[12:13]
	s_waitcnt lgkmcnt(2)
	v_add_f32_e32 v3, v4, v6
	s_waitcnt lgkmcnt(0)
	v_add_f32_e32 v4, v8, v10
	v_add_f32_e32 v3, v3, v4
	v_mul_f32_e32 v3, 0x3bb504f3, v3
	v_bfe_u32 v4, v3, 16, 1
	v_add3_u32 v3, v3, v4, s94
	v_lshl_add_u64 v[12:13], v[0:1], 0, v[12:13]
	global_store_short_d16_hi v[12:13], v3, off
	v_add_f32_e32 v3, v5, v7
	v_add_f32_e32 v4, v9, v11
	v_add_f32_e32 v3, v3, v4
	v_mul_f32_e32 v3, 0x3bb504f3, v3
	v_or_b32_e32 v4, 19, v2
	v_bfe_u32 v5, v3, 16, 1
	v_add3_u32 v3, v3, v5, s94
	v_ashrrev_i32_e32 v5, 31, v4
	v_lshlrev_b64 v[4:5], 10, v[4:5]
	v_lshl_add_u64 v[4:5], v[0:1], 0, v[4:5]
	global_store_short_d16_hi v[4:5], v3, off
	ds_read2st64_b32 v[4:5], v27 offset0:12 offset1:13
	ds_read2st64_b32 v[6:7], v27 offset0:28 offset1:29
	ds_read2st64_b32 v[8:9], v27 offset0:44 offset1:45
	ds_read2st64_b32 v[10:11], v27 offset0:60 offset1:61
	v_or_b32_e32 v12, 24, v2
	v_ashrrev_i32_e32 v13, 31, v12
	v_lshlrev_b64 v[12:13], 10, v[12:13]
	s_waitcnt lgkmcnt(2)
	v_add_f32_e32 v3, v4, v6
	s_waitcnt lgkmcnt(0)
	v_add_f32_e32 v4, v8, v10
	v_add_f32_e32 v3, v3, v4
	v_mul_f32_e32 v3, 0x3bb504f3, v3
	v_bfe_u32 v4, v3, 16, 1
	v_add3_u32 v3, v3, v4, s94
	v_lshl_add_u64 v[12:13], v[0:1], 0, v[12:13]
	global_store_short_d16_hi v[12:13], v3, off
	v_add_f32_e32 v3, v5, v7
	v_add_f32_e32 v4, v9, v11
	v_add_f32_e32 v3, v3, v4
	v_mul_f32_e32 v3, 0x3bb504f3, v3
	v_or_b32_e32 v4, 25, v2
	v_bfe_u32 v5, v3, 16, 1
	v_add3_u32 v3, v3, v5, s94
	v_ashrrev_i32_e32 v5, 31, v4
	v_lshlrev_b64 v[4:5], 10, v[4:5]
	v_lshl_add_u64 v[4:5], v[0:1], 0, v[4:5]
	global_store_short_d16_hi v[4:5], v3, off
	ds_read2st64_b32 v[4:5], v27 offset0:14 offset1:15
	ds_read2st64_b32 v[6:7], v27 offset0:30 offset1:31
	ds_read2st64_b32 v[8:9], v27 offset0:46 offset1:47
	ds_read2st64_b32 v[10:11], v27 offset0:62 offset1:63
	v_or_b32_e32 v12, 26, v2
	v_ashrrev_i32_e32 v13, 31, v12
	v_lshlrev_b64 v[12:13], 10, v[12:13]
	s_waitcnt lgkmcnt(2)
	v_add_f32_e32 v3, v4, v6
	s_waitcnt lgkmcnt(0)
	v_add_f32_e32 v4, v8, v10
	v_add_f32_e32 v3, v3, v4
	v_mul_f32_e32 v3, 0x3bb504f3, v3
	v_bfe_u32 v4, v3, 16, 1
	v_add3_u32 v3, v3, v4, s94
	v_lshl_add_u64 v[12:13], v[0:1], 0, v[12:13]
	global_store_short_d16_hi v[12:13], v3, off
	v_add_f32_e32 v3, v5, v7
	v_add_f32_e32 v4, v9, v11
	v_add_f32_e32 v3, v3, v4
	v_mul_f32_e32 v3, 0x3bb504f3, v3
	v_or_b32_e32 v2, 27, v2
	v_bfe_u32 v4, v3, 16, 1
	v_add3_u32 v4, v3, v4, s94
	v_ashrrev_i32_e32 v3, 31, v2
	v_lshlrev_b64 v[2:3], 10, v[2:3]
	v_lshl_add_u64 v[0:1], v[0:1], 0, v[2:3]
	global_store_short_d16_hi v[0:1], v4, off
	s_branch .LBB0_1234

.LBB0_1341:
	global_load_dwordx4 v[40:43], v[24:25], off offset:-128
	global_load_dwordx4 v[44:47], v[22:23], off offset:-128
	global_load_dwordx4 v[48:51], v[24:25], off offset:-96
	global_load_dwordx4 v[52:55], v[22:23], off offset:-96
	global_load_dwordx4 v[56:59], v[24:25], off offset:-64
	global_load_dwordx4 v[60:63], v[22:23], off offset:-64
	global_load_dwordx4 v[64:67], v[24:25], off offset:-32
	global_load_dwordx4 v[68:71], v[22:23], off offset:-32
	global_load_dwordx4 v[72:75], v[24:25], off
	global_load_dwordx4 v[76:79], v[22:23], off
	global_load_dwordx4 v[80:83], v[24:25], off offset:32
	global_load_dwordx4 v[84:87], v[22:23], off offset:32
	global_load_dwordx4 v[88:91], v[24:25], off offset:64
	global_load_dwordx4 v[92:95], v[22:23], off offset:64
	global_load_dwordx4 v[96:99], v[24:25], off offset:96
	global_load_dwordx4 v[100:103], v[22:23], off offset:96
	s_addk_i32 s22, 0x80
	s_cmpk_gt_u32 s22, 0xef
	v_lshl_add_u64 v[22:23], v[22:23], 0, s[96:97]
	v_lshl_add_u64 v[24:25], v[24:25], 0, s[96:97]
	s_waitcnt vmcnt(14)
	v_mfma_f32_32x32x16_bf16 v[0:15], v[40:43], v[44:47], v[0:15]
	s_waitcnt vmcnt(12)
	v_mfma_f32_32x32x16_bf16 v[0:15], v[48:51], v[52:55], v[0:15]
	s_waitcnt vmcnt(10)
	v_mfma_f32_32x32x16_bf16 v[0:15], v[56:59], v[60:63], v[0:15]
	s_waitcnt vmcnt(8)
	v_mfma_f32_32x32x16_bf16 v[0:15], v[64:67], v[68:71], v[0:15]
	s_waitcnt vmcnt(6)
	v_mfma_f32_32x32x16_bf16 v[0:15], v[72:75], v[76:79], v[0:15]
	s_waitcnt vmcnt(4)
	v_mfma_f32_32x32x16_bf16 v[0:15], v[80:83], v[84:87], v[0:15]
	s_waitcnt vmcnt(2)
	v_mfma_f32_32x32x16_bf16 v[0:15], v[88:91], v[92:95], v[0:15]
	s_waitcnt vmcnt(0)
	v_mfma_f32_32x32x16_bf16 v[0:15], v[96:99], v[100:103], v[0:15]
	s_cbranch_scc0 .LBB0_1341
	s_and_b64 vcc, exec, s[14:15]
	s_nop 9
	ds_write2st64_b32 v28, v0, v1 offset1:1
	ds_write2st64_b32 v28, v2, v3 offset0:2 offset1:3
	ds_write2st64_b32 v28, v4, v5 offset0:4 offset1:5
	ds_write2st64_b32 v28, v6, v7 offset0:6 offset1:7
	ds_write2st64_b32 v28, v8, v9 offset0:8 offset1:9
	ds_write2st64_b32 v28, v10, v11 offset0:10 offset1:11
	ds_write2st64_b32 v28, v12, v13 offset0:12 offset1:13
	ds_write2st64_b32 v28, v14, v15 offset0:14 offset1:15
	s_waitcnt lgkmcnt(0)
	s_barrier
	s_cbranch_vccz .LBB0_1339
	ds_read2st64_b32 v[6:7], v28 offset1:1
	ds_read2st64_b32 v[8:9], v28 offset0:16 offset1:17
	ds_read2st64_b32 v[10:11], v28 offset0:32 offset1:33
	ds_read2st64_b32 v[12:13], v28 offset0:48 offset1:49
	v_or_b32_e32 v4, s5, v29
	v_lshlrev_b64 v[0:1], 1, v[20:21]
	v_lshl_add_u64 v[2:3], s[10:11], 0, v[0:1]
	s_waitcnt lgkmcnt(2)
	v_add_f32_e32 v5, v6, v8
	s_waitcnt lgkmcnt(0)
	v_add_f32_e32 v6, v10, v12
	v_add_f32_e32 v6, v5, v6
	v_ashrrev_i32_e32 v5, 31, v4
	v_lshlrev_b64 v[14:15], 12, v[4:5]
	v_lshl_add_u64 v[14:15], v[2:3], 0, v[14:15]
	global_load_ushort v8, v[14:15], off
	v_lshlrev_b64 v[14:15], 11, v[4:5]
	v_lshl_add_u64 v[14:15], s[12:13], 0, v[14:15]
	v_lshl_add_u64 v[14:15], v[14:15], 0, v[0:1]
	v_add_f32_e32 v5, v7, v9
	s_waitcnt vmcnt(0)
	v_lshlrev_b32_e32 v8, 16, v8
	v_mul_f32_e32 v6, v6, v8
	v_bfe_u32 v8, v6, 16, 1
	v_add3_u32 v6, v6, v8, s94
	global_store_short_d16_hi v[14:15], v6, off
	v_add_f32_e32 v6, v11, v13
	v_add_f32_e32 v5, v5, v6
	v_or_b32_e32 v6, 1, v4
	v_ashrrev_i32_e32 v7, 31, v6
	v_lshlrev_b64 v[8:9], 12, v[6:7]
	v_lshl_add_u64 v[8:9], v[2:3], 0, v[8:9]
	global_load_ushort v8, v[8:9], off
	v_lshlrev_b64 v[6:7], 11, v[6:7]
	v_lshl_add_u64 v[6:7], s[12:13], 0, v[6:7]
	v_lshl_add_u64 v[6:7], v[6:7], 0, v[0:1]
	v_or_b32_e32 v14, 2, v4
	v_ashrrev_i32_e32 v15, 31, v14
	v_lshlrev_b64 v[20:21], 12, v[14:15]
	v_lshl_add_u64 v[20:21], v[2:3], 0, v[20:21]
	v_lshlrev_b64 v[14:15], 11, v[14:15]
	v_lshl_add_u64 v[14:15], s[12:13], 0, v[14:15]
	v_lshl_add_u64 v[14:15], v[14:15], 0, v[0:1]
	s_waitcnt vmcnt(0)
	v_lshlrev_b32_e32 v8, 16, v8
	v_mul_f32_e32 v5, v5, v8
	v_bfe_u32 v8, v5, 16, 1
	v_add3_u32 v5, v5, v8, s94
	global_store_short_d16_hi v[6:7], v5, off
	ds_read2st64_b32 v[6:7], v28 offset0:2 offset1:3
	ds_read2st64_b32 v[8:9], v28 offset0:18 offset1:19
	ds_read2st64_b32 v[10:11], v28 offset0:34 offset1:35
	ds_read2st64_b32 v[12:13], v28 offset0:50 offset1:51
	s_waitcnt lgkmcnt(2)
	v_add_f32_e32 v5, v6, v8
	s_waitcnt lgkmcnt(0)
	v_add_f32_e32 v6, v10, v12
	v_add_f32_e32 v5, v5, v6
	global_load_ushort v6, v[20:21], off
	s_waitcnt vmcnt(0)
	v_lshlrev_b32_e32 v6, 16, v6
	v_mul_f32_e32 v5, v5, v6
	v_bfe_u32 v6, v5, 16, 1
	v_add3_u32 v5, v5, v6, s94
	global_store_short_d16_hi v[14:15], v5, off
	v_add_f32_e32 v5, v7, v9
	v_add_f32_e32 v6, v11, v13
	v_add_f32_e32 v5, v5, v6
	v_or_b32_e32 v6, 3, v4
	v_ashrrev_i32_e32 v7, 31, v6
	v_lshlrev_b64 v[8:9], 12, v[6:7]
	v_lshl_add_u64 v[8:9], v[2:3], 0, v[8:9]
	global_load_ushort v8, v[8:9], off
	v_lshlrev_b64 v[6:7], 11, v[6:7]
	v_lshl_add_u64 v[6:7], s[12:13], 0, v[6:7]
	v_lshl_add_u64 v[6:7], v[6:7], 0, v[0:1]
	v_or_b32_e32 v14, 8, v4
	v_ashrrev_i32_e32 v15, 31, v14
	v_lshlrev_b64 v[20:21], 12, v[14:15]
	v_lshl_add_u64 v[20:21], v[2:3], 0, v[20:21]
	v_lshlrev_b64 v[14:15], 11, v[14:15]
	v_lshl_add_u64 v[14:15], s[12:13], 0, v[14:15]
	v_lshl_add_u64 v[14:15], v[14:15], 0, v[0:1]
	s_waitcnt vmcnt(0)
	v_lshlrev_b32_e32 v8, 16, v8
	v_mul_f32_e32 v5, v5, v8
	v_bfe_u32 v8, v5, 16, 1
	v_add3_u32 v5, v5, v8, s94
	global_store_short_d16_hi v[6:7], v5, off
	ds_read2st64_b32 v[6:7], v28 offset0:4 offset1:5
	ds_read2st64_b32 v[8:9], v28 offset0:20 offset1:21
	ds_read2st64_b32 v[10:11], v28 offset0:36 offset1:37
	ds_read2st64_b32 v[12:13], v28 offset0:52 offset1:53
	s_waitcnt lgkmcnt(2)
	v_add_f32_e32 v5, v6, v8
	s_waitcnt lgkmcnt(0)
	v_add_f32_e32 v6, v10, v12
	v_add_f32_e32 v5, v5, v6
	global_load_ushort v6, v[20:21], off
	s_waitcnt vmcnt(0)
	v_lshlrev_b32_e32 v6, 16, v6
	v_mul_f32_e32 v5, v5, v6
	v_bfe_u32 v6, v5, 16, 1
	v_add3_u32 v5, v5, v6, s94
	global_store_short_d16_hi v[14:15], v5, off
	v_add_f32_e32 v5, v7, v9
	v_add_f32_e32 v6, v11, v13
	v_add_f32_e32 v5, v5, v6
	v_or_b32_e32 v6, 9, v4
	v_ashrrev_i32_e32 v7, 31, v6
	v_lshlrev_b64 v[8:9], 12, v[6:7]
	v_lshl_add_u64 v[8:9], v[2:3], 0, v[8:9]
	global_load_ushort v8, v[8:9], off
	v_lshlrev_b64 v[6:7], 11, v[6:7]
	v_lshl_add_u64 v[6:7], s[12:13], 0, v[6:7]
	v_lshl_add_u64 v[6:7], v[6:7], 0, v[0:1]
	v_or_b32_e32 v14, 10, v4
	v_ashrrev_i32_e32 v15, 31, v14
	v_lshlrev_b64 v[20:21], 12, v[14:15]
	v_lshl_add_u64 v[20:21], v[2:3], 0, v[20:21]
	v_lshlrev_b64 v[14:15], 11, v[14:15]
	v_lshl_add_u64 v[14:15], s[12:13], 0, v[14:15]
	v_lshl_add_u64 v[14:15], v[14:15], 0, v[0:1]
	s_waitcnt vmcnt(0)
	v_lshlrev_b32_e32 v8, 16, v8
	v_mul_f32_e32 v5, v5, v8
	v_bfe_u32 v8, v5, 16, 1
	v_add3_u32 v5, v5, v8, s94
	global_store_short_d16_hi v[6:7], v5, off
	ds_read2st64_b32 v[6:7], v28 offset0:6 offset1:7
	ds_read2st64_b32 v[8:9], v28 offset0:22 offset1:23
	ds_read2st64_b32 v[10:11], v28 offset0:38 offset1:39
	ds_read2st64_b32 v[12:13], v28 offset0:54 offset1:55
	s_waitcnt lgkmcnt(2)
	v_add_f32_e32 v5, v6, v8
	s_waitcnt lgkmcnt(0)
	v_add_f32_e32 v6, v10, v12
	v_add_f32_e32 v5, v5, v6
	global_load_ushort v6, v[20:21], off
	s_waitcnt vmcnt(0)
	v_lshlrev_b32_e32 v6, 16, v6
	v_mul_f32_e32 v5, v5, v6
	v_bfe_u32 v6, v5, 16, 1
	v_add3_u32 v5, v5, v6, s94
	global_store_short_d16_hi v[14:15], v5, off
	v_add_f32_e32 v5, v7, v9
	v_add_f32_e32 v6, v11, v13
	v_add_f32_e32 v5, v5, v6
	v_or_b32_e32 v6, 11, v4
	v_ashrrev_i32_e32 v7, 31, v6
	v_lshlrev_b64 v[8:9], 12, v[6:7]
	v_lshl_add_u64 v[8:9], v[2:3], 0, v[8:9]
	global_load_ushort v8, v[8:9], off
	v_lshlrev_b64 v[6:7], 11, v[6:7]
	v_lshl_add_u64 v[6:7], s[12:13], 0, v[6:7]
	v_lshl_add_u64 v[6:7], v[6:7], 0, v[0:1]
	v_or_b32_e32 v14, 16, v4
	v_ashrrev_i32_e32 v15, 31, v14
	v_lshlrev_b64 v[20:21], 12, v[14:15]
	v_lshl_add_u64 v[20:21], v[2:3], 0, v[20:21]
	v_lshlrev_b64 v[14:15], 11, v[14:15]
	v_lshl_add_u64 v[14:15], s[12:13], 0, v[14:15]
	v_lshl_add_u64 v[14:15], v[14:15], 0, v[0:1]
	s_waitcnt vmcnt(0)
	v_lshlrev_b32_e32 v8, 16, v8
	v_mul_f32_e32 v5, v5, v8
	v_bfe_u32 v8, v5, 16, 1
	v_add3_u32 v5, v5, v8, s94
	global_store_short_d16_hi v[6:7], v5, off
	ds_read2st64_b32 v[6:7], v28 offset0:8 offset1:9
	ds_read2st64_b32 v[8:9], v28 offset0:24 offset1:25
	ds_read2st64_b32 v[10:11], v28 offset0:40 offset1:41
	ds_read2st64_b32 v[12:13], v28 offset0:56 offset1:57
	s_waitcnt lgkmcnt(2)
	v_add_f32_e32 v5, v6, v8
	s_waitcnt lgkmcnt(0)
	v_add_f32_e32 v6, v10, v12
	v_add_f32_e32 v5, v5, v6
	global_load_ushort v6, v[20:21], off
	s_waitcnt vmcnt(0)
	v_lshlrev_b32_e32 v6, 16, v6
	v_mul_f32_e32 v5, v5, v6
	v_bfe_u32 v6, v5, 16, 1
	v_add3_u32 v5, v5, v6, s94
	global_store_short_d16_hi v[14:15], v5, off
	v_add_f32_e32 v5, v7, v9
	v_add_f32_e32 v6, v11, v13
	v_add_f32_e32 v5, v5, v6
	v_or_b32_e32 v6, 17, v4
	v_ashrrev_i32_e32 v7, 31, v6
	v_lshlrev_b64 v[8:9], 12, v[6:7]
	v_lshl_add_u64 v[8:9], v[2:3], 0, v[8:9]
	global_load_ushort v8, v[8:9], off
	v_lshlrev_b64 v[6:7], 11, v[6:7]
	v_lshl_add_u64 v[6:7], s[12:13], 0, v[6:7]
	v_lshl_add_u64 v[6:7], v[6:7], 0, v[0:1]
	v_or_b32_e32 v14, 18, v4
	v_ashrrev_i32_e32 v15, 31, v14
	v_lshlrev_b64 v[20:21], 12, v[14:15]
	v_lshl_add_u64 v[20:21], v[2:3], 0, v[20:21]
	v_lshlrev_b64 v[14:15], 11, v[14:15]
	v_lshl_add_u64 v[14:15], s[12:13], 0, v[14:15]
	v_lshl_add_u64 v[14:15], v[14:15], 0, v[0:1]
	s_waitcnt vmcnt(0)
	v_lshlrev_b32_e32 v8, 16, v8
	v_mul_f32_e32 v5, v5, v8
	v_bfe_u32 v8, v5, 16, 1
	v_add3_u32 v5, v5, v8, s94
	global_store_short_d16_hi v[6:7], v5, off
	ds_read2st64_b32 v[6:7], v28 offset0:10 offset1:11
	ds_read2st64_b32 v[8:9], v28 offset0:26 offset1:27
	ds_read2st64_b32 v[10:11], v28 offset0:42 offset1:43
	ds_read2st64_b32 v[12:13], v28 offset0:58 offset1:59
	s_waitcnt lgkmcnt(2)
	v_add_f32_e32 v5, v6, v8
	s_waitcnt lgkmcnt(0)
	v_add_f32_e32 v6, v10, v12
	v_add_f32_e32 v5, v5, v6
	global_load_ushort v6, v[20:21], off
	s_waitcnt vmcnt(0)
	v_lshlrev_b32_e32 v6, 16, v6
	v_mul_f32_e32 v5, v5, v6
	v_bfe_u32 v6, v5, 16, 1
	v_add3_u32 v5, v5, v6, s94
	global_store_short_d16_hi v[14:15], v5, off
	v_add_f32_e32 v5, v7, v9
	v_add_f32_e32 v6, v11, v13
	v_add_f32_e32 v5, v5, v6
	v_or_b32_e32 v6, 19, v4
	v_ashrrev_i32_e32 v7, 31, v6
	v_lshlrev_b64 v[8:9], 12, v[6:7]
	v_lshl_add_u64 v[8:9], v[2:3], 0, v[8:9]
	global_load_ushort v8, v[8:9], off
	v_lshlrev_b64 v[6:7], 11, v[6:7]
	v_lshl_add_u64 v[6:7], s[12:13], 0, v[6:7]
	v_lshl_add_u64 v[6:7], v[6:7], 0, v[0:1]
	v_or_b32_e32 v14, 24, v4
	v_ashrrev_i32_e32 v15, 31, v14
	v_lshlrev_b64 v[20:21], 12, v[14:15]
	v_lshl_add_u64 v[20:21], v[2:3], 0, v[20:21]
	v_lshlrev_b64 v[14:15], 11, v[14:15]
	v_lshl_add_u64 v[14:15], s[12:13], 0, v[14:15]
	v_lshl_add_u64 v[14:15], v[14:15], 0, v[0:1]
	s_waitcnt vmcnt(0)
	v_lshlrev_b32_e32 v8, 16, v8
	v_mul_f32_e32 v5, v5, v8
	v_bfe_u32 v8, v5, 16, 1
	v_add3_u32 v5, v5, v8, s94
	global_store_short_d16_hi v[6:7], v5, off
	ds_read2st64_b32 v[6:7], v28 offset0:12 offset1:13
	ds_read2st64_b32 v[8:9], v28 offset0:28 offset1:29
	ds_read2st64_b32 v[10:11], v28 offset0:44 offset1:45
	ds_read2st64_b32 v[12:13], v28 offset0:60 offset1:61
	s_waitcnt lgkmcnt(2)
	v_add_f32_e32 v5, v6, v8
	s_waitcnt lgkmcnt(0)
	v_add_f32_e32 v6, v10, v12
	v_add_f32_e32 v5, v5, v6
	global_load_ushort v6, v[20:21], off
	s_waitcnt vmcnt(0)
	v_lshlrev_b32_e32 v6, 16, v6
	v_mul_f32_e32 v5, v5, v6
	v_bfe_u32 v6, v5, 16, 1
	v_add3_u32 v5, v5, v6, s94
	global_store_short_d16_hi v[14:15], v5, off
	v_add_f32_e32 v5, v7, v9
	v_add_f32_e32 v6, v11, v13
	v_add_f32_e32 v5, v5, v6
	v_or_b32_e32 v6, 25, v4
	v_ashrrev_i32_e32 v7, 31, v6
	v_lshlrev_b64 v[8:9], 12, v[6:7]
	v_lshl_add_u64 v[8:9], v[2:3], 0, v[8:9]
	global_load_ushort v8, v[8:9], off
	v_lshlrev_b64 v[6:7], 11, v[6:7]
	v_lshl_add_u64 v[6:7], s[12:13], 0, v[6:7]
	v_lshl_add_u64 v[6:7], v[6:7], 0, v[0:1]
	v_or_b32_e32 v14, 26, v4
	v_ashrrev_i32_e32 v15, 31, v14
	v_lshlrev_b64 v[20:21], 12, v[14:15]
	v_lshl_add_u64 v[20:21], v[2:3], 0, v[20:21]
	v_lshlrev_b64 v[14:15], 11, v[14:15]
	v_lshl_add_u64 v[14:15], s[12:13], 0, v[14:15]
	v_lshl_add_u64 v[14:15], v[14:15], 0, v[0:1]
	v_or_b32_e32 v4, 27, v4
	s_waitcnt vmcnt(0)
	v_lshlrev_b32_e32 v8, 16, v8
	v_mul_f32_e32 v5, v5, v8
	v_bfe_u32 v8, v5, 16, 1
	v_add3_u32 v5, v5, v8, s94
	global_store_short_d16_hi v[6:7], v5, off
	ds_read2st64_b32 v[6:7], v28 offset0:14 offset1:15
	ds_read2st64_b32 v[8:9], v28 offset0:30 offset1:31
	ds_read2st64_b32 v[10:11], v28 offset0:46 offset1:47
	ds_read2st64_b32 v[12:13], v28 offset0:62 offset1:63
	s_waitcnt lgkmcnt(2)
	v_add_f32_e32 v5, v6, v8
	s_waitcnt lgkmcnt(0)
	v_add_f32_e32 v6, v10, v12
	v_add_f32_e32 v5, v5, v6
	global_load_ushort v6, v[20:21], off
	s_waitcnt vmcnt(0)
	v_lshlrev_b32_e32 v6, 16, v6
	v_mul_f32_e32 v5, v5, v6
	v_bfe_u32 v6, v5, 16, 1
	v_add3_u32 v5, v5, v6, s94
	global_store_short_d16_hi v[14:15], v5, off
	v_add_f32_e32 v5, v7, v9
	v_add_f32_e32 v6, v11, v13
	v_add_f32_e32 v8, v5, v6
	v_ashrrev_i32_e32 v5, 31, v4
	v_lshlrev_b64 v[6:7], 12, v[4:5]
	v_lshl_add_u64 v[2:3], v[2:3], 0, v[6:7]
	global_load_ushort v2, v[2:3], off
	s_waitcnt vmcnt(0)
	v_lshlrev_b32_e32 v2, 16, v2
	v_mul_f32_e32 v2, v8, v2
	v_bfe_u32 v3, v2, 16, 1
	v_add3_u32 v6, v2, v3, s94
	v_lshlrev_b64 v[2:3], 11, v[4:5]
	v_lshl_add_u64 v[2:3], s[12:13], 0, v[2:3]
	v_lshl_add_u64 v[0:1], v[2:3], 0, v[0:1]
	global_store_short_d16_hi v[0:1], v6, off
	s_branch .LBB0_1339

.LBB0_1348:
	s_ashr_i32 s4, s0, 31
	s_lshr_b32 s4, s4, 27
	s_add_i32 s4, s0, s4
	s_andn2_b32 s4, s4, 31
	s_sub_i32 s5, s0, s4
	v_or_b32_e32 v0, s4, v22
	v_ashrrev_i32_e32 v1, 31, v0
	v_lshl_or_b32 v20, s5, 5, v22
	v_lshlrev_b64 v[0:1], 10, v[0:1]
	v_ashrrev_i32_e32 v21, 31, v20
	v_lshl_add_u64 v[34:35], v[16:17], 0, v[0:1]
	v_lshlrev_b64 v[0:1], 10, v[20:21]
	v_lshl_add_u64 v[36:37], v[18:19], 0, v[0:1]
	global_load_dwordx4 v[40:43], v[34:35], off
	global_load_dwordx4 v[44:47], v[36:37], off
	global_load_dwordx4 v[48:51], v[34:35], off offset:32
	global_load_dwordx4 v[52:55], v[36:37], off offset:32
	global_load_dwordx4 v[56:59], v[34:35], off offset:64
	global_load_dwordx4 v[60:63], v[36:37], off offset:64
	global_load_dwordx4 v[64:67], v[34:35], off offset:96
	global_load_dwordx4 v[68:71], v[36:37], off offset:96
	global_load_dwordx4 v[72:75], v[34:35], off offset:128
	global_load_dwordx4 v[76:79], v[36:37], off offset:128
	global_load_dwordx4 v[80:83], v[34:35], off offset:160
	global_load_dwordx4 v[84:87], v[36:37], off offset:160
	global_load_dwordx4 v[88:91], v[34:35], off offset:192
	global_load_dwordx4 v[92:95], v[36:37], off offset:192
	global_load_dwordx4 v[96:99], v[34:35], off offset:224
	global_load_dwordx4 v[100:103], v[36:37], off offset:224
	s_andn2_b64 vcc, exec, s[10:11]
	s_waitcnt vmcnt(14)
	v_mfma_f32_32x32x16_bf16 v[0:15], v[40:43], v[44:47], 0
	s_waitcnt vmcnt(12)
	v_mfma_f32_32x32x16_bf16 v[0:15], v[48:51], v[52:55], v[0:15]
	s_waitcnt vmcnt(10)
	v_mfma_f32_32x32x16_bf16 v[0:15], v[56:59], v[60:63], v[0:15]
	s_waitcnt vmcnt(8)
	v_mfma_f32_32x32x16_bf16 v[0:15], v[64:67], v[68:71], v[0:15]
	s_waitcnt vmcnt(6)
	v_mfma_f32_32x32x16_bf16 v[0:15], v[72:75], v[76:79], v[0:15]
	s_waitcnt vmcnt(4)
	v_mfma_f32_32x32x16_bf16 v[0:15], v[80:83], v[84:87], v[0:15]
	s_waitcnt vmcnt(2)
	v_mfma_f32_32x32x16_bf16 v[0:15], v[88:91], v[92:95], v[0:15]
	s_waitcnt vmcnt(0)
	v_mfma_f32_32x32x16_bf16 v[0:15], v[96:99], v[100:103], v[0:15]
	s_nop 11
	ds_write2st64_b32 v23, v0, v1 offset1:1
	ds_write2st64_b32 v23, v2, v3 offset0:2 offset1:3
	ds_write2st64_b32 v23, v4, v5 offset0:4 offset1:5
	ds_write2st64_b32 v23, v6, v7 offset0:6 offset1:7
	ds_write2st64_b32 v23, v8, v9 offset0:8 offset1:9
	ds_write2st64_b32 v23, v10, v11 offset0:10 offset1:11
	ds_write2st64_b32 v23, v12, v13 offset0:12 offset1:13
	ds_write2st64_b32 v23, v14, v15 offset0:14 offset1:15
	s_waitcnt lgkmcnt(0)
	s_barrier
	s_cbranch_vccnz .LBB0_1347
	ds_read2st64_b32 v[6:7], v23 offset1:1
	ds_read2st64_b32 v[8:9], v23 offset0:16 offset1:17
	ds_read2st64_b32 v[10:11], v23 offset0:32 offset1:33
	ds_read2st64_b32 v[12:13], v23 offset0:48 offset1:49
	v_or_b32_e32 v4, s4, v24
	v_lshlrev_b64 v[0:1], 1, v[20:21]
	v_lshl_add_u64 v[2:3], s[8:9], 0, v[0:1]
	s_waitcnt lgkmcnt(2)
	v_add_f32_e32 v5, v6, v8
	s_waitcnt lgkmcnt(0)
	v_add_f32_e32 v6, v10, v12
	v_add_f32_e32 v6, v5, v6
	v_ashrrev_i32_e32 v5, 31, v4
	v_lshlrev_b64 v[14:15], 12, v[4:5]
	v_lshl_add_u64 v[14:15], v[2:3], 0, v[14:15]
	global_load_ushort v8, v[14:15], off
	v_lshlrev_b64 v[14:15], 11, v[4:5]
	v_lshl_add_u64 v[14:15], s[6:7], 0, v[14:15]
	v_lshl_add_u64 v[14:15], v[14:15], 0, v[0:1]
	global_load_ushort v5, v[14:15], off
	s_waitcnt vmcnt(1)
	v_lshlrev_b32_e32 v8, 16, v8
	s_waitcnt vmcnt(0)
	v_lshlrev_b32_e32 v5, 16, v5
	v_fmac_f32_e32 v5, v6, v8
	v_bfe_u32 v6, v5, 16, 1
	v_add3_u32 v5, v5, v6, s94
	global_store_short_d16_hi v[14:15], v5, off
	v_add_f32_e32 v5, v7, v9
	v_add_f32_e32 v6, v11, v13
	v_add_f32_e32 v5, v5, v6
	v_or_b32_e32 v6, 1, v4
	v_ashrrev_i32_e32 v7, 31, v6
	v_lshlrev_b64 v[8:9], 12, v[6:7]
	v_lshlrev_b64 v[6:7], 11, v[6:7]
	v_lshl_add_u64 v[6:7], s[6:7], 0, v[6:7]
	v_lshl_add_u64 v[8:9], v[2:3], 0, v[8:9]
	v_lshl_add_u64 v[6:7], v[6:7], 0, v[0:1]
	global_load_ushort v8, v[8:9], off
	v_or_b32_e32 v14, 2, v4
	global_load_ushort v9, v[6:7], off
	v_ashrrev_i32_e32 v15, 31, v14
	v_lshlrev_b64 v[20:21], 12, v[14:15]
	v_lshlrev_b64 v[14:15], 11, v[14:15]
	v_lshl_add_u64 v[14:15], s[6:7], 0, v[14:15]
	v_lshl_add_u64 v[20:21], v[2:3], 0, v[20:21]
	v_lshl_add_u64 v[14:15], v[14:15], 0, v[0:1]
	s_waitcnt vmcnt(1)
	v_lshlrev_b32_e32 v8, 16, v8
	s_waitcnt vmcnt(0)
	v_lshlrev_b32_e32 v9, 16, v9
	v_fmac_f32_e32 v9, v5, v8
	v_bfe_u32 v5, v9, 16, 1
	v_add3_u32 v5, v9, v5, s94
	global_store_short_d16_hi v[6:7], v5, off
	ds_read2st64_b32 v[6:7], v23 offset0:2 offset1:3
	ds_read2st64_b32 v[8:9], v23 offset0:18 offset1:19
	ds_read2st64_b32 v[10:11], v23 offset0:34 offset1:35
	ds_read2st64_b32 v[12:13], v23 offset0:50 offset1:51
	s_waitcnt lgkmcnt(2)
	v_add_f32_e32 v5, v6, v8
	s_waitcnt lgkmcnt(0)
	v_add_f32_e32 v6, v10, v12
	v_add_f32_e32 v5, v5, v6
	global_load_ushort v6, v[20:21], off
	global_load_ushort v8, v[14:15], off
	s_waitcnt vmcnt(1)
	v_lshlrev_b32_e32 v6, 16, v6
	s_waitcnt vmcnt(0)
	v_lshlrev_b32_e32 v8, 16, v8
	v_fmac_f32_e32 v8, v5, v6
	v_bfe_u32 v5, v8, 16, 1
	v_add3_u32 v5, v8, v5, s94
	global_store_short_d16_hi v[14:15], v5, off
	v_add_f32_e32 v5, v7, v9
	v_add_f32_e32 v6, v11, v13
	v_add_f32_e32 v5, v5, v6
	v_or_b32_e32 v6, 3, v4
	v_ashrrev_i32_e32 v7, 31, v6
	v_lshlrev_b64 v[8:9], 12, v[6:7]
	v_lshlrev_b64 v[6:7], 11, v[6:7]
	v_lshl_add_u64 v[6:7], s[6:7], 0, v[6:7]
	v_lshl_add_u64 v[8:9], v[2:3], 0, v[8:9]
	v_lshl_add_u64 v[6:7], v[6:7], 0, v[0:1]
	global_load_ushort v8, v[8:9], off
	v_or_b32_e32 v14, 8, v4
	global_load_ushort v9, v[6:7], off
	v_ashrrev_i32_e32 v15, 31, v14
	v_lshlrev_b64 v[20:21], 12, v[14:15]
	v_lshlrev_b64 v[14:15], 11, v[14:15]
	v_lshl_add_u64 v[14:15], s[6:7], 0, v[14:15]
	v_lshl_add_u64 v[20:21], v[2:3], 0, v[20:21]
	v_lshl_add_u64 v[14:15], v[14:15], 0, v[0:1]
	s_waitcnt vmcnt(1)
	v_lshlrev_b32_e32 v8, 16, v8
	s_waitcnt vmcnt(0)
	v_lshlrev_b32_e32 v9, 16, v9
	v_fmac_f32_e32 v9, v5, v8
	v_bfe_u32 v5, v9, 16, 1
	v_add3_u32 v5, v9, v5, s94
	global_store_short_d16_hi v[6:7], v5, off
	ds_read2st64_b32 v[6:7], v23 offset0:4 offset1:5
	ds_read2st64_b32 v[8:9], v23 offset0:20 offset1:21
	ds_read2st64_b32 v[10:11], v23 offset0:36 offset1:37
	ds_read2st64_b32 v[12:13], v23 offset0:52 offset1:53
	s_waitcnt lgkmcnt(2)
	v_add_f32_e32 v5, v6, v8
	s_waitcnt lgkmcnt(0)
	v_add_f32_e32 v6, v10, v12
	v_add_f32_e32 v5, v5, v6
	global_load_ushort v6, v[20:21], off
	global_load_ushort v8, v[14:15], off
	s_waitcnt vmcnt(1)
	v_lshlrev_b32_e32 v6, 16, v6
	s_waitcnt vmcnt(0)
	v_lshlrev_b32_e32 v8, 16, v8
	v_fmac_f32_e32 v8, v5, v6
	v_bfe_u32 v5, v8, 16, 1
	v_add3_u32 v5, v8, v5, s94
	global_store_short_d16_hi v[14:15], v5, off
	v_add_f32_e32 v5, v7, v9
	v_add_f32_e32 v6, v11, v13
	v_add_f32_e32 v5, v5, v6
	v_or_b32_e32 v6, 9, v4
	v_ashrrev_i32_e32 v7, 31, v6
	v_lshlrev_b64 v[8:9], 12, v[6:7]
	v_lshlrev_b64 v[6:7], 11, v[6:7]
	v_lshl_add_u64 v[6:7], s[6:7], 0, v[6:7]
	v_lshl_add_u64 v[8:9], v[2:3], 0, v[8:9]
	v_lshl_add_u64 v[6:7], v[6:7], 0, v[0:1]
	global_load_ushort v8, v[8:9], off
	v_or_b32_e32 v14, 10, v4
	global_load_ushort v9, v[6:7], off
	v_ashrrev_i32_e32 v15, 31, v14
	v_lshlrev_b64 v[20:21], 12, v[14:15]
	v_lshlrev_b64 v[14:15], 11, v[14:15]
	v_lshl_add_u64 v[14:15], s[6:7], 0, v[14:15]
	v_lshl_add_u64 v[20:21], v[2:3], 0, v[20:21]
	v_lshl_add_u64 v[14:15], v[14:15], 0, v[0:1]
	s_waitcnt vmcnt(1)
	v_lshlrev_b32_e32 v8, 16, v8
	s_waitcnt vmcnt(0)
	v_lshlrev_b32_e32 v9, 16, v9
	v_fmac_f32_e32 v9, v5, v8
	v_bfe_u32 v5, v9, 16, 1
	v_add3_u32 v5, v9, v5, s94
	global_store_short_d16_hi v[6:7], v5, off
	ds_read2st64_b32 v[6:7], v23 offset0:6 offset1:7
	ds_read2st64_b32 v[8:9], v23 offset0:22 offset1:23
	ds_read2st64_b32 v[10:11], v23 offset0:38 offset1:39
	ds_read2st64_b32 v[12:13], v23 offset0:54 offset1:55
	s_waitcnt lgkmcnt(2)
	v_add_f32_e32 v5, v6, v8
	s_waitcnt lgkmcnt(0)
	v_add_f32_e32 v6, v10, v12
	v_add_f32_e32 v5, v5, v6
	global_load_ushort v6, v[20:21], off
	global_load_ushort v8, v[14:15], off
	s_waitcnt vmcnt(1)
	v_lshlrev_b32_e32 v6, 16, v6
	s_waitcnt vmcnt(0)
	v_lshlrev_b32_e32 v8, 16, v8
	v_fmac_f32_e32 v8, v5, v6
	v_bfe_u32 v5, v8, 16, 1
	v_add3_u32 v5, v8, v5, s94
	global_store_short_d16_hi v[14:15], v5, off
	v_add_f32_e32 v5, v7, v9
	v_add_f32_e32 v6, v11, v13
	v_add_f32_e32 v5, v5, v6
	v_or_b32_e32 v6, 11, v4
	v_ashrrev_i32_e32 v7, 31, v6
	v_lshlrev_b64 v[8:9], 12, v[6:7]
	v_lshlrev_b64 v[6:7], 11, v[6:7]
	v_lshl_add_u64 v[6:7], s[6:7], 0, v[6:7]
	v_lshl_add_u64 v[8:9], v[2:3], 0, v[8:9]
	v_lshl_add_u64 v[6:7], v[6:7], 0, v[0:1]
	global_load_ushort v8, v[8:9], off
	v_or_b32_e32 v14, 16, v4
	global_load_ushort v9, v[6:7], off
	v_ashrrev_i32_e32 v15, 31, v14
	v_lshlrev_b64 v[20:21], 12, v[14:15]
	v_lshlrev_b64 v[14:15], 11, v[14:15]
	v_lshl_add_u64 v[14:15], s[6:7], 0, v[14:15]
	v_lshl_add_u64 v[20:21], v[2:3], 0, v[20:21]
	v_lshl_add_u64 v[14:15], v[14:15], 0, v[0:1]
	s_waitcnt vmcnt(1)
	v_lshlrev_b32_e32 v8, 16, v8
	s_waitcnt vmcnt(0)
	v_lshlrev_b32_e32 v9, 16, v9
	v_fmac_f32_e32 v9, v5, v8
	v_bfe_u32 v5, v9, 16, 1
	v_add3_u32 v5, v9, v5, s94
	global_store_short_d16_hi v[6:7], v5, off
	ds_read2st64_b32 v[6:7], v23 offset0:8 offset1:9
	ds_read2st64_b32 v[8:9], v23 offset0:24 offset1:25
	ds_read2st64_b32 v[10:11], v23 offset0:40 offset1:41
	ds_read2st64_b32 v[12:13], v23 offset0:56 offset1:57
	s_waitcnt lgkmcnt(2)
	v_add_f32_e32 v5, v6, v8
	s_waitcnt lgkmcnt(0)
	v_add_f32_e32 v6, v10, v12
	v_add_f32_e32 v5, v5, v6
	global_load_ushort v6, v[20:21], off
	global_load_ushort v8, v[14:15], off
	s_waitcnt vmcnt(1)
	v_lshlrev_b32_e32 v6, 16, v6
	s_waitcnt vmcnt(0)
	v_lshlrev_b32_e32 v8, 16, v8
	v_fmac_f32_e32 v8, v5, v6
	v_bfe_u32 v5, v8, 16, 1
	v_add3_u32 v5, v8, v5, s94
	global_store_short_d16_hi v[14:15], v5, off
	v_add_f32_e32 v5, v7, v9
	v_add_f32_e32 v6, v11, v13
	v_add_f32_e32 v5, v5, v6
	v_or_b32_e32 v6, 17, v4
	v_ashrrev_i32_e32 v7, 31, v6
	v_lshlrev_b64 v[8:9], 12, v[6:7]
	v_lshlrev_b64 v[6:7], 11, v[6:7]
	v_lshl_add_u64 v[6:7], s[6:7], 0, v[6:7]
	v_lshl_add_u64 v[8:9], v[2:3], 0, v[8:9]
	v_lshl_add_u64 v[6:7], v[6:7], 0, v[0:1]
	global_load_ushort v8, v[8:9], off
	v_or_b32_e32 v14, 18, v4
	global_load_ushort v9, v[6:7], off
	v_ashrrev_i32_e32 v15, 31, v14
	v_lshlrev_b64 v[20:21], 12, v[14:15]
	v_lshlrev_b64 v[14:15], 11, v[14:15]
	v_lshl_add_u64 v[14:15], s[6:7], 0, v[14:15]
	v_lshl_add_u64 v[20:21], v[2:3], 0, v[20:21]
	v_lshl_add_u64 v[14:15], v[14:15], 0, v[0:1]
	s_waitcnt vmcnt(1)
	v_lshlrev_b32_e32 v8, 16, v8
	s_waitcnt vmcnt(0)
	v_lshlrev_b32_e32 v9, 16, v9
	v_fmac_f32_e32 v9, v5, v8
	v_bfe_u32 v5, v9, 16, 1
	v_add3_u32 v5, v9, v5, s94
	global_store_short_d16_hi v[6:7], v5, off
	ds_read2st64_b32 v[6:7], v23 offset0:10 offset1:11
	ds_read2st64_b32 v[8:9], v23 offset0:26 offset1:27
	ds_read2st64_b32 v[10:11], v23 offset0:42 offset1:43
	ds_read2st64_b32 v[12:13], v23 offset0:58 offset1:59
	s_waitcnt lgkmcnt(2)
	v_add_f32_e32 v5, v6, v8
	s_waitcnt lgkmcnt(0)
	v_add_f32_e32 v6, v10, v12
	v_add_f32_e32 v5, v5, v6
	global_load_ushort v6, v[20:21], off
	global_load_ushort v8, v[14:15], off
	s_waitcnt vmcnt(1)
	v_lshlrev_b32_e32 v6, 16, v6
	s_waitcnt vmcnt(0)
	v_lshlrev_b32_e32 v8, 16, v8
	v_fmac_f32_e32 v8, v5, v6
	v_bfe_u32 v5, v8, 16, 1
	v_add3_u32 v5, v8, v5, s94
	global_store_short_d16_hi v[14:15], v5, off
	v_add_f32_e32 v5, v7, v9
	v_add_f32_e32 v6, v11, v13
	v_add_f32_e32 v5, v5, v6
	v_or_b32_e32 v6, 19, v4
	v_ashrrev_i32_e32 v7, 31, v6
	v_lshlrev_b64 v[8:9], 12, v[6:7]
	v_lshlrev_b64 v[6:7], 11, v[6:7]
	v_lshl_add_u64 v[6:7], s[6:7], 0, v[6:7]
	v_lshl_add_u64 v[8:9], v[2:3], 0, v[8:9]
	v_lshl_add_u64 v[6:7], v[6:7], 0, v[0:1]
	global_load_ushort v8, v[8:9], off
	v_or_b32_e32 v14, 24, v4
	global_load_ushort v9, v[6:7], off
	v_ashrrev_i32_e32 v15, 31, v14
	v_lshlrev_b64 v[20:21], 12, v[14:15]
	v_lshlrev_b64 v[14:15], 11, v[14:15]
	v_lshl_add_u64 v[14:15], s[6:7], 0, v[14:15]
	v_lshl_add_u64 v[20:21], v[2:3], 0, v[20:21]
	v_lshl_add_u64 v[14:15], v[14:15], 0, v[0:1]
	s_waitcnt vmcnt(1)
	v_lshlrev_b32_e32 v8, 16, v8
	s_waitcnt vmcnt(0)
	v_lshlrev_b32_e32 v9, 16, v9
	v_fmac_f32_e32 v9, v5, v8
	v_bfe_u32 v5, v9, 16, 1
	v_add3_u32 v5, v9, v5, s94
	global_store_short_d16_hi v[6:7], v5, off
	ds_read2st64_b32 v[6:7], v23 offset0:12 offset1:13
	ds_read2st64_b32 v[8:9], v23 offset0:28 offset1:29
	ds_read2st64_b32 v[10:11], v23 offset0:44 offset1:45
	ds_read2st64_b32 v[12:13], v23 offset0:60 offset1:61
	s_waitcnt lgkmcnt(2)
	v_add_f32_e32 v5, v6, v8
	s_waitcnt lgkmcnt(0)
	v_add_f32_e32 v6, v10, v12
	v_add_f32_e32 v5, v5, v6
	global_load_ushort v6, v[20:21], off
	global_load_ushort v8, v[14:15], off
	s_waitcnt vmcnt(1)
	v_lshlrev_b32_e32 v6, 16, v6
	s_waitcnt vmcnt(0)
	v_lshlrev_b32_e32 v8, 16, v8
	v_fmac_f32_e32 v8, v5, v6
	v_bfe_u32 v5, v8, 16, 1
	v_add3_u32 v5, v8, v5, s94
	global_store_short_d16_hi v[14:15], v5, off
	v_add_f32_e32 v5, v7, v9
	v_add_f32_e32 v6, v11, v13
	v_add_f32_e32 v5, v5, v6
	v_or_b32_e32 v6, 25, v4
	v_ashrrev_i32_e32 v7, 31, v6
	v_lshlrev_b64 v[8:9], 12, v[6:7]
	v_lshlrev_b64 v[6:7], 11, v[6:7]
	v_lshl_add_u64 v[6:7], s[6:7], 0, v[6:7]
	v_lshl_add_u64 v[8:9], v[2:3], 0, v[8:9]
	v_lshl_add_u64 v[6:7], v[6:7], 0, v[0:1]
	global_load_ushort v8, v[8:9], off
	v_or_b32_e32 v14, 26, v4
	global_load_ushort v9, v[6:7], off
	v_ashrrev_i32_e32 v15, 31, v14
	v_lshlrev_b64 v[20:21], 12, v[14:15]
	v_lshlrev_b64 v[14:15], 11, v[14:15]
	v_lshl_add_u64 v[14:15], s[6:7], 0, v[14:15]
	v_lshl_add_u64 v[20:21], v[2:3], 0, v[20:21]
	v_lshl_add_u64 v[14:15], v[14:15], 0, v[0:1]
	s_waitcnt vmcnt(1)
	v_lshlrev_b32_e32 v8, 16, v8
	s_waitcnt vmcnt(0)
	v_lshlrev_b32_e32 v9, 16, v9
	v_fmac_f32_e32 v9, v5, v8
	v_bfe_u32 v5, v9, 16, 1
	v_add3_u32 v5, v9, v5, s94
	global_store_short_d16_hi v[6:7], v5, off
	ds_read2st64_b32 v[6:7], v23 offset0:14 offset1:15
	ds_read2st64_b32 v[8:9], v23 offset0:30 offset1:31
	ds_read2st64_b32 v[10:11], v23 offset0:46 offset1:47
	ds_read2st64_b32 v[12:13], v23 offset0:62 offset1:63
	s_waitcnt lgkmcnt(2)
	v_add_f32_e32 v5, v6, v8
	s_waitcnt lgkmcnt(0)
	v_add_f32_e32 v6, v10, v12
	v_add_f32_e32 v5, v5, v6
	global_load_ushort v6, v[20:21], off
	global_load_ushort v8, v[14:15], off
	s_waitcnt vmcnt(1)
	v_lshlrev_b32_e32 v6, 16, v6
	s_waitcnt vmcnt(0)
	v_lshlrev_b32_e32 v8, 16, v8
	v_fmac_f32_e32 v8, v5, v6
	v_bfe_u32 v5, v8, 16, 1
	v_add3_u32 v5, v8, v5, s94
	global_store_short_d16_hi v[14:15], v5, off
	v_add_f32_e32 v5, v7, v9
	v_add_f32_e32 v6, v11, v13
	v_add_f32_e32 v5, v5, v6
	v_or_b32_e32 v6, 27, v4
	v_ashrrev_i32_e32 v7, 31, v6
	v_lshlrev_b64 v[8:9], 12, v[6:7]
	v_lshlrev_b64 v[6:7], 11, v[6:7]
	v_lshl_add_u64 v[6:7], s[6:7], 0, v[6:7]
	v_lshl_add_u64 v[2:3], v[2:3], 0, v[8:9]
	v_lshl_add_u64 v[0:1], v[6:7], 0, v[0:1]
	global_load_ushort v2, v[2:3], off
	s_waitcnt vmcnt(0)
	v_lshlrev_b32_e32 v2, 16, v2
	global_load_ushort v3, v[0:1], off
	s_waitcnt vmcnt(0)
	v_lshlrev_b32_e32 v3, 16, v3
	v_fmac_f32_e32 v3, v5, v2
	v_bfe_u32 v2, v3, 16, 1
	v_add3_u32 v2, v3, v2, s94
	global_store_short_d16_hi v[0:1], v2, off
	s_branch .LBB0_1347

.LBB0_1478:
	global_load_dwordx4 v[76:79], v[24:25], off offset:-128
	global_load_dwordx4 v[80:83], v[22:23], off offset:-128
	global_load_dwordx4 v[84:87], v[24:25], off offset:-96
	global_load_dwordx4 v[88:91], v[22:23], off offset:-96
	global_load_dwordx4 v[92:95], v[24:25], off offset:-64
	global_load_dwordx4 v[96:99], v[22:23], off offset:-64
	global_load_dwordx4 v[100:103], v[24:25], off offset:-32
	global_load_dwordx4 v[104:107], v[22:23], off offset:-32
	global_load_dwordx4 v[108:111], v[24:25], off
	global_load_dwordx4 v[112:115], v[22:23], off
	global_load_dwordx4 v[116:119], v[24:25], off offset:32
	global_load_dwordx4 v[120:123], v[22:23], off offset:32
	global_load_dwordx4 v[124:127], v[24:25], off offset:64
	global_load_dwordx4 v[128:131], v[22:23], off offset:64
	global_load_dwordx4 v[132:135], v[24:25], off offset:96
	global_load_dwordx4 v[136:139], v[22:23], off offset:96
	s_addk_i32 s9, 0x80
	s_cmpk_gt_u32 s9, 0xef
	v_lshl_add_u64 v[22:23], v[22:23], 0, s[96:97]
	v_lshl_add_u64 v[24:25], v[24:25], 0, s[96:97]
	s_waitcnt vmcnt(14)
	v_mfma_f32_32x32x16_bf16 v[0:15], v[76:79], v[80:83], v[0:15]
	s_waitcnt vmcnt(12)
	v_mfma_f32_32x32x16_bf16 v[0:15], v[84:87], v[88:91], v[0:15]
	s_waitcnt vmcnt(10)
	v_mfma_f32_32x32x16_bf16 v[0:15], v[92:95], v[96:99], v[0:15]
	s_waitcnt vmcnt(8)
	v_mfma_f32_32x32x16_bf16 v[0:15], v[100:103], v[104:107], v[0:15]
	s_waitcnt vmcnt(6)
	v_mfma_f32_32x32x16_bf16 v[0:15], v[108:111], v[112:115], v[0:15]
	s_waitcnt vmcnt(4)
	v_mfma_f32_32x32x16_bf16 v[0:15], v[116:119], v[120:123], v[0:15]
	s_waitcnt vmcnt(2)
	v_mfma_f32_32x32x16_bf16 v[0:15], v[124:127], v[128:131], v[0:15]
	s_waitcnt vmcnt(0)
	v_mfma_f32_32x32x16_bf16 v[0:15], v[132:135], v[136:139], v[0:15]
	s_cbranch_scc0 .LBB0_1478
	s_and_b64 vcc, exec, s[6:7]
	s_nop 9
	ds_write2st64_b32 v27, v0, v1 offset1:1
	ds_write2st64_b32 v27, v2, v3 offset0:2 offset1:3
	ds_write2st64_b32 v27, v4, v5 offset0:4 offset1:5
	ds_write2st64_b32 v27, v6, v7 offset0:6 offset1:7
	ds_write2st64_b32 v27, v8, v9 offset0:8 offset1:9
	ds_write2st64_b32 v27, v10, v11 offset0:10 offset1:11
	ds_write2st64_b32 v27, v12, v13 offset0:12 offset1:13
	ds_write2st64_b32 v27, v14, v15 offset0:14 offset1:15
	s_waitcnt lgkmcnt(0)
	s_barrier
	s_cbranch_vccz .LBB0_1476
	ds_read2st64_b32 v[6:7], v27 offset1:1
	ds_read2st64_b32 v[8:9], v27 offset0:16 offset1:17
	ds_read2st64_b32 v[10:11], v27 offset0:32 offset1:33
	ds_read2st64_b32 v[12:13], v27 offset0:48 offset1:49
	v_or_b32_e32 v4, s8, v28
	v_lshlrev_b64 v[2:3], 2, v[20:21]
	v_lshl_add_u64 v[0:1], s[0:1], 0, v[2:3]
	s_waitcnt lgkmcnt(2)
	v_add_f32_e32 v5, v6, v8
	s_waitcnt lgkmcnt(0)
	v_add_f32_e32 v6, v10, v12
	v_add_f32_e32 v6, v5, v6
	v_ashrrev_i32_e32 v5, 31, v4
	v_lshlrev_b64 v[14:15], 12, v[4:5]
	v_lshl_add_u64 v[14:15], s[12:13], 0, v[14:15]
	v_lshl_add_u64 v[14:15], v[14:15], 0, v[2:3]
	global_load_dword v5, v[14:15], off
	global_load_dword v8, v[0:1], off
	s_waitcnt vmcnt(0)
	v_fmac_f32_e32 v5, v6, v8
	global_store_dword v[14:15], v5, off
	v_add_f32_e32 v5, v7, v9
	v_add_f32_e32 v6, v11, v13
	v_add_f32_e32 v5, v5, v6
	v_or_b32_e32 v6, 1, v4
	v_ashrrev_i32_e32 v7, 31, v6
	v_lshlrev_b64 v[6:7], 12, v[6:7]
	v_lshl_add_u64 v[6:7], s[12:13], 0, v[6:7]
	v_lshl_add_u64 v[6:7], v[6:7], 0, v[2:3]
	global_load_dword v8, v[6:7], off
	global_load_dword v9, v[0:1], off
	v_or_b32_e32 v14, 2, v4
	v_ashrrev_i32_e32 v15, 31, v14
	v_lshlrev_b64 v[14:15], 12, v[14:15]
	v_lshl_add_u64 v[14:15], s[12:13], 0, v[14:15]
	v_lshl_add_u64 v[14:15], v[14:15], 0, v[2:3]
	s_waitcnt vmcnt(0)
	v_fmac_f32_e32 v8, v5, v9
	global_store_dword v[6:7], v8, off
	ds_read2st64_b32 v[6:7], v27 offset0:2 offset1:3
	ds_read2st64_b32 v[8:9], v27 offset0:18 offset1:19
	ds_read2st64_b32 v[10:11], v27 offset0:34 offset1:35
	ds_read2st64_b32 v[12:13], v27 offset0:50 offset1:51
	s_waitcnt lgkmcnt(2)
	v_add_f32_e32 v5, v6, v8
	s_waitcnt lgkmcnt(0)
	v_add_f32_e32 v6, v10, v12
	v_add_f32_e32 v5, v5, v6
	global_load_dword v6, v[14:15], off
	global_load_dword v8, v[0:1], off
	s_waitcnt vmcnt(0)
	v_fmac_f32_e32 v6, v5, v8
	global_store_dword v[14:15], v6, off
	v_add_f32_e32 v5, v7, v9
	v_add_f32_e32 v6, v11, v13
	v_add_f32_e32 v5, v5, v6
	v_or_b32_e32 v6, 3, v4
	v_ashrrev_i32_e32 v7, 31, v6
	v_lshlrev_b64 v[6:7], 12, v[6:7]
	v_lshl_add_u64 v[6:7], s[12:13], 0, v[6:7]
	v_lshl_add_u64 v[6:7], v[6:7], 0, v[2:3]
	global_load_dword v8, v[6:7], off
	global_load_dword v9, v[0:1], off
	v_or_b32_e32 v14, 8, v4
	v_ashrrev_i32_e32 v15, 31, v14
	v_lshlrev_b64 v[14:15], 12, v[14:15]
	v_lshl_add_u64 v[14:15], s[12:13], 0, v[14:15]
	v_lshl_add_u64 v[14:15], v[14:15], 0, v[2:3]
	s_waitcnt vmcnt(0)
	v_fmac_f32_e32 v8, v5, v9
	global_store_dword v[6:7], v8, off
	ds_read2st64_b32 v[6:7], v27 offset0:4 offset1:5
	ds_read2st64_b32 v[8:9], v27 offset0:20 offset1:21
	ds_read2st64_b32 v[10:11], v27 offset0:36 offset1:37
	ds_read2st64_b32 v[12:13], v27 offset0:52 offset1:53
	s_waitcnt lgkmcnt(2)
	v_add_f32_e32 v5, v6, v8
	s_waitcnt lgkmcnt(0)
	v_add_f32_e32 v6, v10, v12
	v_add_f32_e32 v5, v5, v6
	global_load_dword v6, v[14:15], off
	global_load_dword v8, v[0:1], off
	s_waitcnt vmcnt(0)
	v_fmac_f32_e32 v6, v5, v8
	global_store_dword v[14:15], v6, off
	v_add_f32_e32 v5, v7, v9
	v_add_f32_e32 v6, v11, v13
	v_add_f32_e32 v5, v5, v6
	v_or_b32_e32 v6, 9, v4
	v_ashrrev_i32_e32 v7, 31, v6
	v_lshlrev_b64 v[6:7], 12, v[6:7]
	v_lshl_add_u64 v[6:7], s[12:13], 0, v[6:7]
	v_lshl_add_u64 v[6:7], v[6:7], 0, v[2:3]
	global_load_dword v8, v[6:7], off
	global_load_dword v9, v[0:1], off
	v_or_b32_e32 v14, 10, v4
	v_ashrrev_i32_e32 v15, 31, v14
	v_lshlrev_b64 v[14:15], 12, v[14:15]
	v_lshl_add_u64 v[14:15], s[12:13], 0, v[14:15]
	v_lshl_add_u64 v[14:15], v[14:15], 0, v[2:3]
	s_waitcnt vmcnt(0)
	v_fmac_f32_e32 v8, v5, v9
	global_store_dword v[6:7], v8, off
	ds_read2st64_b32 v[6:7], v27 offset0:6 offset1:7
	ds_read2st64_b32 v[8:9], v27 offset0:22 offset1:23
	ds_read2st64_b32 v[10:11], v27 offset0:38 offset1:39
	ds_read2st64_b32 v[12:13], v27 offset0:54 offset1:55
	s_waitcnt lgkmcnt(2)
	v_add_f32_e32 v5, v6, v8
	s_waitcnt lgkmcnt(0)
	v_add_f32_e32 v6, v10, v12
	v_add_f32_e32 v5, v5, v6
	global_load_dword v6, v[14:15], off
	global_load_dword v8, v[0:1], off
	s_waitcnt vmcnt(0)
	v_fmac_f32_e32 v6, v5, v8
	global_store_dword v[14:15], v6, off
	v_add_f32_e32 v5, v7, v9
	v_add_f32_e32 v6, v11, v13
	v_add_f32_e32 v5, v5, v6
	v_or_b32_e32 v6, 11, v4
	v_ashrrev_i32_e32 v7, 31, v6
	v_lshlrev_b64 v[6:7], 12, v[6:7]
	v_lshl_add_u64 v[6:7], s[12:13], 0, v[6:7]
	v_lshl_add_u64 v[6:7], v[6:7], 0, v[2:3]
	global_load_dword v8, v[6:7], off
	global_load_dword v9, v[0:1], off
	v_or_b32_e32 v14, 16, v4
	v_ashrrev_i32_e32 v15, 31, v14
	v_lshlrev_b64 v[14:15], 12, v[14:15]
	v_lshl_add_u64 v[14:15], s[12:13], 0, v[14:15]
	v_lshl_add_u64 v[14:15], v[14:15], 0, v[2:3]
	s_waitcnt vmcnt(0)
	v_fmac_f32_e32 v8, v5, v9
	global_store_dword v[6:7], v8, off
	ds_read2st64_b32 v[6:7], v27 offset0:8 offset1:9
	ds_read2st64_b32 v[8:9], v27 offset0:24 offset1:25
	ds_read2st64_b32 v[10:11], v27 offset0:40 offset1:41
	ds_read2st64_b32 v[12:13], v27 offset0:56 offset1:57
	s_waitcnt lgkmcnt(2)
	v_add_f32_e32 v5, v6, v8
	s_waitcnt lgkmcnt(0)
	v_add_f32_e32 v6, v10, v12
	v_add_f32_e32 v5, v5, v6
	global_load_dword v6, v[14:15], off
	global_load_dword v8, v[0:1], off
	s_waitcnt vmcnt(0)
	v_fmac_f32_e32 v6, v5, v8
	global_store_dword v[14:15], v6, off
	v_add_f32_e32 v5, v7, v9
	v_add_f32_e32 v6, v11, v13
	v_add_f32_e32 v5, v5, v6
	v_or_b32_e32 v6, 17, v4
	v_ashrrev_i32_e32 v7, 31, v6
	v_lshlrev_b64 v[6:7], 12, v[6:7]
	v_lshl_add_u64 v[6:7], s[12:13], 0, v[6:7]
	v_lshl_add_u64 v[6:7], v[6:7], 0, v[2:3]
	global_load_dword v8, v[6:7], off
	global_load_dword v9, v[0:1], off
	v_or_b32_e32 v14, 18, v4
	v_ashrrev_i32_e32 v15, 31, v14
	v_lshlrev_b64 v[14:15], 12, v[14:15]
	v_lshl_add_u64 v[14:15], s[12:13], 0, v[14:15]
	v_lshl_add_u64 v[14:15], v[14:15], 0, v[2:3]
	s_waitcnt vmcnt(0)
	v_fmac_f32_e32 v8, v5, v9
	global_store_dword v[6:7], v8, off
	ds_read2st64_b32 v[6:7], v27 offset0:10 offset1:11
	ds_read2st64_b32 v[8:9], v27 offset0:26 offset1:27
	ds_read2st64_b32 v[10:11], v27 offset0:42 offset1:43
	ds_read2st64_b32 v[12:13], v27 offset0:58 offset1:59
	s_waitcnt lgkmcnt(2)
	v_add_f32_e32 v5, v6, v8
	s_waitcnt lgkmcnt(0)
	v_add_f32_e32 v6, v10, v12
	v_add_f32_e32 v5, v5, v6
	global_load_dword v6, v[14:15], off
	global_load_dword v8, v[0:1], off
	s_waitcnt vmcnt(0)
	v_fmac_f32_e32 v6, v5, v8
	global_store_dword v[14:15], v6, off
	v_add_f32_e32 v5, v7, v9
	v_add_f32_e32 v6, v11, v13
	v_add_f32_e32 v5, v5, v6
	v_or_b32_e32 v6, 19, v4
	v_ashrrev_i32_e32 v7, 31, v6
	v_lshlrev_b64 v[6:7], 12, v[6:7]
	v_lshl_add_u64 v[6:7], s[12:13], 0, v[6:7]
	v_lshl_add_u64 v[6:7], v[6:7], 0, v[2:3]
	global_load_dword v8, v[6:7], off
	global_load_dword v9, v[0:1], off
	v_or_b32_e32 v14, 24, v4
	v_ashrrev_i32_e32 v15, 31, v14
	v_lshlrev_b64 v[14:15], 12, v[14:15]
	v_lshl_add_u64 v[14:15], s[12:13], 0, v[14:15]
	v_lshl_add_u64 v[14:15], v[14:15], 0, v[2:3]
	s_waitcnt vmcnt(0)
	v_fmac_f32_e32 v8, v5, v9
	global_store_dword v[6:7], v8, off
	ds_read2st64_b32 v[6:7], v27 offset0:12 offset1:13
	ds_read2st64_b32 v[8:9], v27 offset0:28 offset1:29
	ds_read2st64_b32 v[10:11], v27 offset0:44 offset1:45
	ds_read2st64_b32 v[12:13], v27 offset0:60 offset1:61
	s_waitcnt lgkmcnt(2)
	v_add_f32_e32 v5, v6, v8
	s_waitcnt lgkmcnt(0)
	v_add_f32_e32 v6, v10, v12
	v_add_f32_e32 v5, v5, v6
	global_load_dword v6, v[14:15], off
	global_load_dword v8, v[0:1], off
	s_waitcnt vmcnt(0)
	v_fmac_f32_e32 v6, v5, v8
	global_store_dword v[14:15], v6, off
	v_add_f32_e32 v5, v7, v9
	v_add_f32_e32 v6, v11, v13
	v_add_f32_e32 v5, v5, v6
	v_or_b32_e32 v6, 25, v4
	v_ashrrev_i32_e32 v7, 31, v6
	v_lshlrev_b64 v[6:7], 12, v[6:7]
	v_lshl_add_u64 v[6:7], s[12:13], 0, v[6:7]
	v_lshl_add_u64 v[6:7], v[6:7], 0, v[2:3]
	global_load_dword v8, v[6:7], off
	global_load_dword v9, v[0:1], off
	v_or_b32_e32 v14, 26, v4
	v_ashrrev_i32_e32 v15, 31, v14
	v_lshlrev_b64 v[14:15], 12, v[14:15]
	v_lshl_add_u64 v[14:15], s[12:13], 0, v[14:15]
	v_lshl_add_u64 v[14:15], v[14:15], 0, v[2:3]
	v_or_b32_e32 v4, 27, v4
	s_waitcnt vmcnt(0)
	v_fmac_f32_e32 v8, v5, v9
	global_store_dword v[6:7], v8, off
	ds_read2st64_b32 v[6:7], v27 offset0:14 offset1:15
	ds_read2st64_b32 v[8:9], v27 offset0:30 offset1:31
	ds_read2st64_b32 v[10:11], v27 offset0:46 offset1:47
	ds_read2st64_b32 v[12:13], v27 offset0:62 offset1:63
	s_waitcnt lgkmcnt(2)
	v_add_f32_e32 v5, v6, v8
	s_waitcnt lgkmcnt(0)
	v_add_f32_e32 v6, v10, v12
	v_add_f32_e32 v5, v5, v6
	global_load_dword v6, v[14:15], off
	global_load_dword v8, v[0:1], off
	s_waitcnt vmcnt(0)
	v_fmac_f32_e32 v6, v5, v8
	global_store_dword v[14:15], v6, off
	v_add_f32_e32 v5, v7, v9
	v_add_f32_e32 v6, v11, v13
	v_add_f32_e32 v6, v5, v6
	v_ashrrev_i32_e32 v5, 31, v4
	v_lshlrev_b64 v[4:5], 12, v[4:5]
	v_lshl_add_u64 v[4:5], s[12:13], 0, v[4:5]
	v_lshl_add_u64 v[2:3], v[4:5], 0, v[2:3]
	global_load_dword v4, v[2:3], off
	s_nop 0
	global_load_dword v0, v[0:1], off
	s_waitcnt vmcnt(0)
	v_fmac_f32_e32 v4, v6, v0
	global_store_dword v[2:3], v4, off
	s_branch .LBB0_1476

.LBB0_1758:
	s_ashr_i32 s8, s0, 31
	s_lshr_b32 s8, s8, 27
	s_add_i32 s8, s0, s8
	s_andn2_b32 s8, s8, 31
	s_sub_i32 s9, s0, s8
	v_or_b32_e32 v0, s8, v26
	v_mad_i64_i32 v[24:25], s[10:11], v0, s87, v[16:17]
	v_lshl_or_b32 v20, s9, 5, v26
	v_mad_i64_i32 v[22:23], s[10:11], v20, s87, v[18:19]
	global_load_dwordx4 v[76:79], v[24:25], off
	global_load_dwordx4 v[80:83], v[22:23], off
	global_load_dwordx4 v[84:87], v[24:25], off offset:32
	global_load_dwordx4 v[88:91], v[22:23], off offset:32
	global_load_dwordx4 v[92:95], v[24:25], off offset:64
	global_load_dwordx4 v[96:99], v[22:23], off offset:64
	global_load_dwordx4 v[100:103], v[24:25], off offset:96
	global_load_dwordx4 v[104:107], v[22:23], off offset:96
	global_load_dwordx4 v[108:111], v[24:25], off offset:128
	global_load_dwordx4 v[112:115], v[22:23], off offset:128
	global_load_dwordx4 v[116:119], v[24:25], off offset:160
	global_load_dwordx4 v[120:123], v[22:23], off offset:160
	global_load_dwordx4 v[124:127], v[24:25], off offset:192
	global_load_dwordx4 v[128:131], v[22:23], off offset:192
	global_load_dwordx4 v[132:135], v[24:25], off offset:224
	global_load_dwordx4 v[136:139], v[22:23], off offset:224
	global_load_dwordx4 v[140:143], v[24:25], off offset:256
	global_load_dwordx4 v[144:147], v[22:23], off offset:256
	global_load_dwordx4 v[148:151], v[24:25], off offset:288
	global_load_dwordx4 v[152:155], v[22:23], off offset:288
	global_load_dwordx4 v[156:159], v[24:25], off offset:320
	global_load_dwordx4 v[160:163], v[22:23], off offset:320
	global_load_dwordx4 v[164:167], v[24:25], off offset:352
	global_load_dwordx4 v[168:171], v[22:23], off offset:352
	global_load_dwordx4 v[172:175], v[24:25], off offset:384
	global_load_dwordx4 v[176:179], v[22:23], off offset:384
	global_load_dwordx4 v[180:183], v[24:25], off offset:416
	global_load_dwordx4 v[184:187], v[22:23], off offset:416
	global_load_dwordx4 v[188:191], v[24:25], off offset:448
	global_load_dwordx4 v[192:195], v[22:23], off offset:448
	s_andn2_b64 vcc, exec, s[6:7]
	s_waitcnt vmcnt(28)
	v_mfma_f32_32x32x16_bf16 v[0:15], v[76:79], v[80:83], 0
	global_load_dwordx4 v[76:79], v[24:25], off offset:480
	global_load_dwordx4 v[80:83], v[22:23], off offset:480
	s_waitcnt vmcnt(28)
	v_mfma_f32_32x32x16_bf16 v[0:15], v[84:87], v[88:91], v[0:15]
	global_load_dwordx4 v[84:87], v[24:25], off offset:512
	global_load_dwordx4 v[88:91], v[22:23], off offset:512
	s_waitcnt vmcnt(28)
	v_mfma_f32_32x32x16_bf16 v[0:15], v[92:95], v[96:99], v[0:15]
	global_load_dwordx4 v[92:95], v[24:25], off offset:544
	global_load_dwordx4 v[96:99], v[22:23], off offset:544
	s_waitcnt vmcnt(28)
	v_mfma_f32_32x32x16_bf16 v[0:15], v[100:103], v[104:107], v[0:15]
	global_load_dwordx4 v[100:103], v[24:25], off offset:576
	global_load_dwordx4 v[104:107], v[22:23], off offset:576
	s_waitcnt vmcnt(28)
	v_mfma_f32_32x32x16_bf16 v[0:15], v[108:111], v[112:115], v[0:15]
	global_load_dwordx4 v[108:111], v[24:25], off offset:608
	global_load_dwordx4 v[112:115], v[22:23], off offset:608
	s_waitcnt vmcnt(28)
	v_mfma_f32_32x32x16_bf16 v[0:15], v[116:119], v[120:123], v[0:15]
	global_load_dwordx4 v[116:119], v[24:25], off offset:640
	global_load_dwordx4 v[120:123], v[22:23], off offset:640
	s_waitcnt vmcnt(28)
	v_mfma_f32_32x32x16_bf16 v[0:15], v[124:127], v[128:131], v[0:15]
	global_load_dwordx4 v[124:127], v[24:25], off offset:672
	global_load_dwordx4 v[128:131], v[22:23], off offset:672
	s_waitcnt vmcnt(28)
	v_mfma_f32_32x32x16_bf16 v[0:15], v[132:135], v[136:139], v[0:15]
	global_load_dwordx4 v[132:135], v[24:25], off offset:704
	global_load_dwordx4 v[136:139], v[22:23], off offset:704
	s_waitcnt vmcnt(28)
	v_mfma_f32_32x32x16_bf16 v[0:15], v[140:143], v[144:147], v[0:15]
	global_load_dwordx4 v[140:143], v[24:25], off offset:736
	global_load_dwordx4 v[144:147], v[22:23], off offset:736
	s_waitcnt vmcnt(28)
	v_mfma_f32_32x32x16_bf16 v[0:15], v[148:151], v[152:155], v[0:15]
	global_load_dwordx4 v[148:151], v[24:25], off offset:768
	global_load_dwordx4 v[152:155], v[22:23], off offset:768
	s_waitcnt vmcnt(28)
	v_mfma_f32_32x32x16_bf16 v[0:15], v[156:159], v[160:163], v[0:15]
	global_load_dwordx4 v[156:159], v[24:25], off offset:800
	global_load_dwordx4 v[160:163], v[22:23], off offset:800
	s_waitcnt vmcnt(28)
	v_mfma_f32_32x32x16_bf16 v[0:15], v[164:167], v[168:171], v[0:15]
	global_load_dwordx4 v[164:167], v[24:25], off offset:832
	global_load_dwordx4 v[168:171], v[22:23], off offset:832
	s_waitcnt vmcnt(28)
	v_mfma_f32_32x32x16_bf16 v[0:15], v[172:175], v[176:179], v[0:15]
	global_load_dwordx4 v[172:175], v[24:25], off offset:864
	global_load_dwordx4 v[176:179], v[22:23], off offset:864
	s_waitcnt vmcnt(28)
	v_mfma_f32_32x32x16_bf16 v[0:15], v[180:183], v[184:187], v[0:15]
	global_load_dwordx4 v[180:183], v[24:25], off offset:896
	global_load_dwordx4 v[184:187], v[22:23], off offset:896
	s_waitcnt vmcnt(28)
	v_mfma_f32_32x32x16_bf16 v[0:15], v[188:191], v[192:195], v[0:15]
	global_load_dwordx4 v[188:191], v[24:25], off offset:928
	global_load_dwordx4 v[192:195], v[22:23], off offset:928
	s_waitcnt vmcnt(28)
	v_mfma_f32_32x32x16_bf16 v[0:15], v[76:79], v[80:83], v[0:15]
	global_load_dwordx4 v[76:79], v[24:25], off offset:960
	global_load_dwordx4 v[80:83], v[22:23], off offset:960
	s_waitcnt vmcnt(28)
	v_mfma_f32_32x32x16_bf16 v[0:15], v[84:87], v[88:91], v[0:15]
	global_load_dwordx4 v[84:87], v[24:25], off offset:992
	global_load_dwordx4 v[88:91], v[22:23], off offset:992
	s_waitcnt vmcnt(28)
	v_mfma_f32_32x32x16_bf16 v[0:15], v[92:95], v[96:99], v[0:15]
	global_load_dwordx4 v[92:95], v[24:25], off offset:1024
	global_load_dwordx4 v[96:99], v[22:23], off offset:1024
	s_waitcnt vmcnt(28)
	v_mfma_f32_32x32x16_bf16 v[0:15], v[100:103], v[104:107], v[0:15]
	global_load_dwordx4 v[100:103], v[24:25], off offset:1056
	global_load_dwordx4 v[104:107], v[22:23], off offset:1056
	s_waitcnt vmcnt(28)
	v_mfma_f32_32x32x16_bf16 v[0:15], v[108:111], v[112:115], v[0:15]
	global_load_dwordx4 v[108:111], v[24:25], off offset:1088
	global_load_dwordx4 v[112:115], v[22:23], off offset:1088
	s_waitcnt vmcnt(28)
	v_mfma_f32_32x32x16_bf16 v[0:15], v[116:119], v[120:123], v[0:15]
	global_load_dwordx4 v[116:119], v[24:25], off offset:1120
	global_load_dwordx4 v[120:123], v[22:23], off offset:1120
	s_waitcnt vmcnt(28)
	v_mfma_f32_32x32x16_bf16 v[0:15], v[124:127], v[128:131], v[0:15]
	global_load_dwordx4 v[124:127], v[24:25], off offset:1152
	global_load_dwordx4 v[128:131], v[22:23], off offset:1152
	s_waitcnt vmcnt(28)
	v_mfma_f32_32x32x16_bf16 v[0:15], v[132:135], v[136:139], v[0:15]
	global_load_dwordx4 v[132:135], v[24:25], off offset:1184
	global_load_dwordx4 v[136:139], v[22:23], off offset:1184
	s_waitcnt vmcnt(28)
	v_mfma_f32_32x32x16_bf16 v[0:15], v[140:143], v[144:147], v[0:15]
	global_load_dwordx4 v[140:143], v[24:25], off offset:1216
	global_load_dwordx4 v[144:147], v[22:23], off offset:1216
	s_waitcnt vmcnt(28)
	v_mfma_f32_32x32x16_bf16 v[0:15], v[148:151], v[152:155], v[0:15]
	global_load_dwordx4 v[148:151], v[24:25], off offset:1248
	global_load_dwordx4 v[152:155], v[22:23], off offset:1248
	s_waitcnt vmcnt(28)
	v_mfma_f32_32x32x16_bf16 v[0:15], v[156:159], v[160:163], v[0:15]
	global_load_dwordx4 v[156:159], v[24:25], off offset:1280
	global_load_dwordx4 v[160:163], v[22:23], off offset:1280
	s_waitcnt vmcnt(28)
	v_mfma_f32_32x32x16_bf16 v[0:15], v[164:167], v[168:171], v[0:15]
	global_load_dwordx4 v[164:167], v[24:25], off offset:1312
	global_load_dwordx4 v[168:171], v[22:23], off offset:1312
	s_waitcnt vmcnt(28)
	v_mfma_f32_32x32x16_bf16 v[0:15], v[172:175], v[176:179], v[0:15]
	global_load_dwordx4 v[172:175], v[24:25], off offset:1344
	global_load_dwordx4 v[176:179], v[22:23], off offset:1344
	s_waitcnt vmcnt(28)
	v_mfma_f32_32x32x16_bf16 v[0:15], v[180:183], v[184:187], v[0:15]
	global_load_dwordx4 v[180:183], v[24:25], off offset:1376
	global_load_dwordx4 v[184:187], v[22:23], off offset:1376
	s_waitcnt vmcnt(28)
	v_mfma_f32_32x32x16_bf16 v[0:15], v[188:191], v[192:195], v[0:15]
	s_waitcnt vmcnt(26)
	v_mfma_f32_32x32x16_bf16 v[0:15], v[76:79], v[80:83], v[0:15]
	s_waitcnt vmcnt(24)
	v_mfma_f32_32x32x16_bf16 v[0:15], v[84:87], v[88:91], v[0:15]
	s_waitcnt vmcnt(22)
	v_mfma_f32_32x32x16_bf16 v[0:15], v[92:95], v[96:99], v[0:15]
	s_waitcnt vmcnt(20)
	v_mfma_f32_32x32x16_bf16 v[0:15], v[100:103], v[104:107], v[0:15]
	s_waitcnt vmcnt(18)
	v_mfma_f32_32x32x16_bf16 v[0:15], v[108:111], v[112:115], v[0:15]
	s_waitcnt vmcnt(16)
	v_mfma_f32_32x32x16_bf16 v[0:15], v[116:119], v[120:123], v[0:15]
	s_waitcnt vmcnt(14)
	v_mfma_f32_32x32x16_bf16 v[0:15], v[124:127], v[128:131], v[0:15]
	s_waitcnt vmcnt(12)
	v_mfma_f32_32x32x16_bf16 v[0:15], v[132:135], v[136:139], v[0:15]
	s_waitcnt vmcnt(10)
	v_mfma_f32_32x32x16_bf16 v[0:15], v[140:143], v[144:147], v[0:15]
	s_waitcnt vmcnt(8)
	v_mfma_f32_32x32x16_bf16 v[0:15], v[148:151], v[152:155], v[0:15]
	s_waitcnt vmcnt(6)
	v_mfma_f32_32x32x16_bf16 v[0:15], v[156:159], v[160:163], v[0:15]
	s_waitcnt vmcnt(4)
	v_mfma_f32_32x32x16_bf16 v[0:15], v[164:167], v[168:171], v[0:15]
	s_waitcnt vmcnt(2)
	v_mfma_f32_32x32x16_bf16 v[0:15], v[172:175], v[176:179], v[0:15]
	s_waitcnt vmcnt(0)
	v_mfma_f32_32x32x16_bf16 v[0:15], v[180:183], v[184:187], v[0:15]
	s_nop 11
	ds_write2st64_b32 v27, v0, v1 offset1:1
	ds_write2st64_b32 v27, v2, v3 offset0:2 offset1:3
	ds_write2st64_b32 v27, v4, v5 offset0:4 offset1:5
	ds_write2st64_b32 v27, v6, v7 offset0:6 offset1:7
	ds_write2st64_b32 v27, v8, v9 offset0:8 offset1:9
	ds_write2st64_b32 v27, v10, v11 offset0:10 offset1:11
	ds_write2st64_b32 v27, v12, v13 offset0:12 offset1:13
	ds_write2st64_b32 v27, v14, v15 offset0:14 offset1:15
	s_waitcnt lgkmcnt(0)
	s_barrier
	s_cbranch_vccnz .LBB0_1757
	ds_read2st64_b32 v[6:7], v27 offset1:1
	ds_read2st64_b32 v[8:9], v27 offset0:16 offset1:17
	ds_read2st64_b32 v[10:11], v27 offset0:32 offset1:33
	ds_read2st64_b32 v[12:13], v27 offset0:48 offset1:49
	v_or_b32_e32 v4, s8, v28
	v_ashrrev_i32_e32 v21, 31, v20
	v_lshlrev_b64 v[2:3], 2, v[20:21]
	s_waitcnt lgkmcnt(2)
	v_add_f32_e32 v5, v6, v8
	s_waitcnt lgkmcnt(0)
	v_add_f32_e32 v6, v10, v12
	v_add_f32_e32 v6, v5, v6
	v_ashrrev_i32_e32 v5, 31, v4
	v_lshlrev_b64 v[14:15], 12, v[4:5]
	v_lshl_add_u64 v[14:15], s[34:35], 0, v[14:15]
	v_lshl_add_u64 v[14:15], v[14:15], 0, v[2:3]
	v_lshl_add_u64 v[0:1], s[4:5], 0, v[2:3]
	global_load_dword v5, v[14:15], off
	global_load_dword v8, v[0:1], off
	s_waitcnt vmcnt(0)
	v_mul_f32_e32 v8, 0.5, v8
	v_fmac_f32_e32 v5, v6, v8
	global_store_dword v[14:15], v5, off
	v_add_f32_e32 v5, v7, v9
	v_add_f32_e32 v6, v11, v13
	v_add_f32_e32 v5, v5, v6
	v_or_b32_e32 v6, 1, v4
	v_ashrrev_i32_e32 v7, 31, v6
	v_lshlrev_b64 v[6:7], 12, v[6:7]
	v_lshl_add_u64 v[6:7], s[34:35], 0, v[6:7]
	v_lshl_add_u64 v[6:7], v[6:7], 0, v[2:3]
	global_load_dword v8, v[6:7], off
	global_load_dword v9, v[0:1], off
	v_or_b32_e32 v14, 2, v4
	v_ashrrev_i32_e32 v15, 31, v14
	v_lshlrev_b64 v[14:15], 12, v[14:15]
	v_lshl_add_u64 v[14:15], s[34:35], 0, v[14:15]
	v_lshl_add_u64 v[14:15], v[14:15], 0, v[2:3]
	s_waitcnt vmcnt(0)
	v_mul_f32_e32 v9, 0.5, v9
	v_fmac_f32_e32 v8, v5, v9
	global_store_dword v[6:7], v8, off
	ds_read2st64_b32 v[6:7], v27 offset0:2 offset1:3
	ds_read2st64_b32 v[8:9], v27 offset0:18 offset1:19
	ds_read2st64_b32 v[10:11], v27 offset0:34 offset1:35
	ds_read2st64_b32 v[12:13], v27 offset0:50 offset1:51
	s_waitcnt lgkmcnt(2)
	v_add_f32_e32 v5, v6, v8
	s_waitcnt lgkmcnt(0)
	v_add_f32_e32 v6, v10, v12
	v_add_f32_e32 v5, v5, v6
	global_load_dword v6, v[14:15], off
	global_load_dword v8, v[0:1], off
	s_waitcnt vmcnt(0)
	v_mul_f32_e32 v8, 0.5, v8
	v_fmac_f32_e32 v6, v5, v8
	global_store_dword v[14:15], v6, off
	v_add_f32_e32 v5, v7, v9
	v_add_f32_e32 v6, v11, v13
	v_add_f32_e32 v5, v5, v6
	v_or_b32_e32 v6, 3, v4
	v_ashrrev_i32_e32 v7, 31, v6
	v_lshlrev_b64 v[6:7], 12, v[6:7]
	v_lshl_add_u64 v[6:7], s[34:35], 0, v[6:7]
	v_lshl_add_u64 v[6:7], v[6:7], 0, v[2:3]
	global_load_dword v8, v[6:7], off
	global_load_dword v9, v[0:1], off
	v_or_b32_e32 v14, 8, v4
	v_ashrrev_i32_e32 v15, 31, v14
	v_lshlrev_b64 v[14:15], 12, v[14:15]
	v_lshl_add_u64 v[14:15], s[34:35], 0, v[14:15]
	v_lshl_add_u64 v[14:15], v[14:15], 0, v[2:3]
	s_waitcnt vmcnt(0)
	v_mul_f32_e32 v9, 0.5, v9
	v_fmac_f32_e32 v8, v5, v9
	global_store_dword v[6:7], v8, off
	ds_read2st64_b32 v[6:7], v27 offset0:4 offset1:5
	ds_read2st64_b32 v[8:9], v27 offset0:20 offset1:21
	ds_read2st64_b32 v[10:11], v27 offset0:36 offset1:37
	ds_read2st64_b32 v[12:13], v27 offset0:52 offset1:53
	s_waitcnt lgkmcnt(2)
	v_add_f32_e32 v5, v6, v8
	s_waitcnt lgkmcnt(0)
	v_add_f32_e32 v6, v10, v12
	v_add_f32_e32 v5, v5, v6
	global_load_dword v6, v[14:15], off
	global_load_dword v8, v[0:1], off
	s_waitcnt vmcnt(0)
	v_mul_f32_e32 v8, 0.5, v8
	v_fmac_f32_e32 v6, v5, v8
	global_store_dword v[14:15], v6, off
	v_add_f32_e32 v5, v7, v9
	v_add_f32_e32 v6, v11, v13
	v_add_f32_e32 v5, v5, v6
	v_or_b32_e32 v6, 9, v4
	v_ashrrev_i32_e32 v7, 31, v6
	v_lshlrev_b64 v[6:7], 12, v[6:7]
	v_lshl_add_u64 v[6:7], s[34:35], 0, v[6:7]
	v_lshl_add_u64 v[6:7], v[6:7], 0, v[2:3]
	global_load_dword v8, v[6:7], off
	global_load_dword v9, v[0:1], off
	v_or_b32_e32 v14, 10, v4
	v_ashrrev_i32_e32 v15, 31, v14
	v_lshlrev_b64 v[14:15], 12, v[14:15]
	v_lshl_add_u64 v[14:15], s[34:35], 0, v[14:15]
	v_lshl_add_u64 v[14:15], v[14:15], 0, v[2:3]
	s_waitcnt vmcnt(0)
	v_mul_f32_e32 v9, 0.5, v9
	v_fmac_f32_e32 v8, v5, v9
	global_store_dword v[6:7], v8, off
	ds_read2st64_b32 v[6:7], v27 offset0:6 offset1:7
	ds_read2st64_b32 v[8:9], v27 offset0:22 offset1:23
	ds_read2st64_b32 v[10:11], v27 offset0:38 offset1:39
	ds_read2st64_b32 v[12:13], v27 offset0:54 offset1:55
	s_waitcnt lgkmcnt(2)
	v_add_f32_e32 v5, v6, v8
	s_waitcnt lgkmcnt(0)
	v_add_f32_e32 v6, v10, v12
	v_add_f32_e32 v5, v5, v6
	global_load_dword v6, v[14:15], off
	global_load_dword v8, v[0:1], off
	s_waitcnt vmcnt(0)
	v_mul_f32_e32 v8, 0.5, v8
	v_fmac_f32_e32 v6, v5, v8
	global_store_dword v[14:15], v6, off
	v_add_f32_e32 v5, v7, v9
	v_add_f32_e32 v6, v11, v13
	v_add_f32_e32 v5, v5, v6
	v_or_b32_e32 v6, 11, v4
	v_ashrrev_i32_e32 v7, 31, v6
	v_lshlrev_b64 v[6:7], 12, v[6:7]
	v_lshl_add_u64 v[6:7], s[34:35], 0, v[6:7]
	v_lshl_add_u64 v[6:7], v[6:7], 0, v[2:3]
	global_load_dword v8, v[6:7], off
	global_load_dword v9, v[0:1], off
	v_or_b32_e32 v14, 16, v4
	v_ashrrev_i32_e32 v15, 31, v14
	v_lshlrev_b64 v[14:15], 12, v[14:15]
	v_lshl_add_u64 v[14:15], s[34:35], 0, v[14:15]
	v_lshl_add_u64 v[14:15], v[14:15], 0, v[2:3]
	s_waitcnt vmcnt(0)
	v_mul_f32_e32 v9, 0.5, v9
	v_fmac_f32_e32 v8, v5, v9
	global_store_dword v[6:7], v8, off
	ds_read2st64_b32 v[6:7], v27 offset0:8 offset1:9
	ds_read2st64_b32 v[8:9], v27 offset0:24 offset1:25
	ds_read2st64_b32 v[10:11], v27 offset0:40 offset1:41
	ds_read2st64_b32 v[12:13], v27 offset0:56 offset1:57
	s_waitcnt lgkmcnt(2)
	v_add_f32_e32 v5, v6, v8
	s_waitcnt lgkmcnt(0)
	v_add_f32_e32 v6, v10, v12
	v_add_f32_e32 v5, v5, v6
	global_load_dword v6, v[14:15], off
	global_load_dword v8, v[0:1], off
	s_waitcnt vmcnt(0)
	v_mul_f32_e32 v8, 0.5, v8
	v_fmac_f32_e32 v6, v5, v8
	global_store_dword v[14:15], v6, off
	v_add_f32_e32 v5, v7, v9
	v_add_f32_e32 v6, v11, v13
	v_add_f32_e32 v5, v5, v6
	v_or_b32_e32 v6, 17, v4
	v_ashrrev_i32_e32 v7, 31, v6
	v_lshlrev_b64 v[6:7], 12, v[6:7]
	v_lshl_add_u64 v[6:7], s[34:35], 0, v[6:7]
	v_lshl_add_u64 v[6:7], v[6:7], 0, v[2:3]
	global_load_dword v8, v[6:7], off
	global_load_dword v9, v[0:1], off
	v_or_b32_e32 v14, 18, v4
	v_ashrrev_i32_e32 v15, 31, v14
	v_lshlrev_b64 v[14:15], 12, v[14:15]
	v_lshl_add_u64 v[14:15], s[34:35], 0, v[14:15]
	v_lshl_add_u64 v[14:15], v[14:15], 0, v[2:3]
	s_waitcnt vmcnt(0)
	v_mul_f32_e32 v9, 0.5, v9
	v_fmac_f32_e32 v8, v5, v9
	global_store_dword v[6:7], v8, off
	ds_read2st64_b32 v[6:7], v27 offset0:10 offset1:11
	ds_read2st64_b32 v[8:9], v27 offset0:26 offset1:27
	ds_read2st64_b32 v[10:11], v27 offset0:42 offset1:43
	ds_read2st64_b32 v[12:13], v27 offset0:58 offset1:59
	s_waitcnt lgkmcnt(2)
	v_add_f32_e32 v5, v6, v8
	s_waitcnt lgkmcnt(0)
	v_add_f32_e32 v6, v10, v12
	v_add_f32_e32 v5, v5, v6
	global_load_dword v6, v[14:15], off
	global_load_dword v8, v[0:1], off
	s_waitcnt vmcnt(0)
	v_mul_f32_e32 v8, 0.5, v8
	v_fmac_f32_e32 v6, v5, v8
	global_store_dword v[14:15], v6, off
	v_add_f32_e32 v5, v7, v9
	v_add_f32_e32 v6, v11, v13
	v_add_f32_e32 v5, v5, v6
	v_or_b32_e32 v6, 19, v4
	v_ashrrev_i32_e32 v7, 31, v6
	v_lshlrev_b64 v[6:7], 12, v[6:7]
	v_lshl_add_u64 v[6:7], s[34:35], 0, v[6:7]
	v_lshl_add_u64 v[6:7], v[6:7], 0, v[2:3]
	global_load_dword v8, v[6:7], off
	global_load_dword v9, v[0:1], off
	v_or_b32_e32 v14, 24, v4
	v_ashrrev_i32_e32 v15, 31, v14
	v_lshlrev_b64 v[14:15], 12, v[14:15]
	v_lshl_add_u64 v[14:15], s[34:35], 0, v[14:15]
	v_lshl_add_u64 v[14:15], v[14:15], 0, v[2:3]
	s_waitcnt vmcnt(0)
	v_mul_f32_e32 v9, 0.5, v9
	v_fmac_f32_e32 v8, v5, v9
	global_store_dword v[6:7], v8, off
	ds_read2st64_b32 v[6:7], v27 offset0:12 offset1:13
	ds_read2st64_b32 v[8:9], v27 offset0:28 offset1:29
	ds_read2st64_b32 v[10:11], v27 offset0:44 offset1:45
	ds_read2st64_b32 v[12:13], v27 offset0:60 offset1:61
	s_waitcnt lgkmcnt(2)
	v_add_f32_e32 v5, v6, v8
	s_waitcnt lgkmcnt(0)
	v_add_f32_e32 v6, v10, v12
	v_add_f32_e32 v5, v5, v6
	global_load_dword v6, v[14:15], off
	global_load_dword v8, v[0:1], off
	s_waitcnt vmcnt(0)
	v_mul_f32_e32 v8, 0.5, v8
	v_fmac_f32_e32 v6, v5, v8
	global_store_dword v[14:15], v6, off
	v_add_f32_e32 v5, v7, v9
	v_add_f32_e32 v6, v11, v13
	v_add_f32_e32 v5, v5, v6
	v_or_b32_e32 v6, 25, v4
	v_ashrrev_i32_e32 v7, 31, v6
	v_lshlrev_b64 v[6:7], 12, v[6:7]
	v_lshl_add_u64 v[6:7], s[34:35], 0, v[6:7]
	v_lshl_add_u64 v[6:7], v[6:7], 0, v[2:3]
	global_load_dword v8, v[6:7], off
	global_load_dword v9, v[0:1], off
	v_or_b32_e32 v14, 26, v4
	v_ashrrev_i32_e32 v15, 31, v14
	v_lshlrev_b64 v[14:15], 12, v[14:15]
	v_lshl_add_u64 v[14:15], s[34:35], 0, v[14:15]
	v_lshl_add_u64 v[14:15], v[14:15], 0, v[2:3]
	v_or_b32_e32 v4, 27, v4
	s_waitcnt vmcnt(0)
	v_mul_f32_e32 v9, 0.5, v9
	v_fmac_f32_e32 v8, v5, v9
	global_store_dword v[6:7], v8, off
	ds_read2st64_b32 v[6:7], v27 offset0:14 offset1:15
	ds_read2st64_b32 v[8:9], v27 offset0:30 offset1:31
	ds_read2st64_b32 v[10:11], v27 offset0:46 offset1:47
	ds_read2st64_b32 v[12:13], v27 offset0:62 offset1:63
	s_waitcnt lgkmcnt(2)
	v_add_f32_e32 v5, v6, v8
	s_waitcnt lgkmcnt(0)
	v_add_f32_e32 v6, v10, v12
	v_add_f32_e32 v5, v5, v6
	global_load_dword v6, v[14:15], off
	global_load_dword v8, v[0:1], off
	s_waitcnt vmcnt(0)
	v_mul_f32_e32 v8, 0.5, v8
	v_fmac_f32_e32 v6, v5, v8
	global_store_dword v[14:15], v6, off
	v_add_f32_e32 v5, v7, v9
	v_add_f32_e32 v6, v11, v13
	v_add_f32_e32 v6, v5, v6
	v_ashrrev_i32_e32 v5, 31, v4
	v_lshlrev_b64 v[4:5], 12, v[4:5]
	v_lshl_add_u64 v[4:5], s[34:35], 0, v[4:5]
	v_lshl_add_u64 v[2:3], v[4:5], 0, v[2:3]
	global_load_dword v4, v[2:3], off
	s_nop 0
	global_load_dword v0, v[0:1], off
	s_waitcnt vmcnt(0)
	v_mul_f32_e32 v0, 0.5, v0
	v_fmac_f32_e32 v4, v6, v0
	global_store_dword v[2:3], v4, off
	s_branch .LBB0_1757
